# remaining rsqrt sites (e64-mask forms, gMLP rstd) lose the never-taken denormal rescale too
# baseline (speedup 1.0000x reference)
; #define LAS __attribute__((address_space(3)))
; __device__ __forceinline__ float bflo(unsigned u) { return __uint_as_float(u << 16); }
; __device__ __forceinline__ float bfhi(unsigned u) { return __uint_as_float(u & 0xffff0000u); }
; __device__ __forceinline__ unsigned pk2(float lo, float hi) { f32x2_t v = {lo, hi}; bf16x2_t b = __builtin_convertvector(v, bf16x2_t); return __builtin_bit_cast(unsigned, b); }
; __device__ __forceinline__ void attn_phase(LAS unsigned char* lds, const bf16* PROJ, const bf16* Ygate, bf16* OG0, bf16* OG1, bf16* OG2, float* LSE, const float* qnw, const float* knw, int bx, int G) {
;     ...
;         const int sub = t & 15, gi = (t >> 4) % 3, bh = t / 48, h = bh & 15, bl = bh >> 4;
;         const int sh = 2 * gi, d = 1 << sh, r = sub & (d - 1), n = sub >> sh;
;         const float ad = exp2f(-8.f * (float)(gi * 16 + h + 1) / 48.f) * (float)d;
;         bf16* OG = gi == 0 ? OG0 : (gi == 1 ? OG1 : OG2);
;         {
;             const f32x4 kw0 = *(const f32x4*)(knw + gi * 64 + 8 * oct), kw1 = *(const f32x4*)(knw + gi * 64 + 8 * oct + 4);
; #pragma unroll
;             for (int jj = 0; jj < 4; ++jj) {
;                 const int key = (tid >> 3) + 64 * jj; const v4u kq = kr[half][jj];
;                 float kf[8] = {bflo(kq.x), bfhi(kq.x), bflo(kq.y), bfhi(kq.y), bflo(kq.z), bfhi(kq.z), bflo(kq.w), bfhi(kq.w)};
;                 float ss = 0.f;
; #pragma unroll
;                 for (int e = 0; e < 8; ++e) ss += kf[e] * kf[e];
;                 ss += __shfl_xor(ss, 1); ss += __shfl_xor(ss, 2); ss += __shfl_xor(ss, 4);
;                 const float rs = rsqrtf(ss * (1.f / 64.f) + EPS);
;                 v4u ko; ko.x = pk2(kf[0] * rs * kw0[0], kf[1] * rs * kw0[1]); ko.y = pk2(kf[2] * rs * kw0[2], kf[3] * rs * kw0[3]);
;                 ko.z = pk2(kf[4] * rs * kw1[0], kf[5] * rs * kw1[1]); ko.w = pk2(kf[6] * rs * kw1[2], kf[7] * rs * kw1[3]);
;                 *(LAS v4u*)(Ks + key * 72 + 8 * oct) = ko;
;                 *(LAS v4u*)(Vs + key * 80 + 8 * oct) = vr[half][jj];
.LBB0_269:
	s_ashr_i32 s0, s51, 4
	s_mul_hi_i32 s1, s0, 0x55555556
	s_lshr_b32 s2, s1, 31
	s_add_i32 s1, s1, s2
	s_mul_i32 s1, s1, 3
	s_sub_i32 s2, s0, s1
	s_mul_hi_i32 s0, s51, 0x2aaaaaab
	s_lshl_b32 s3, s2, 1
	s_and_b32 s20, s51, 15
	s_lshr_b32 s1, s0, 31
	s_ashr_i32 s21, s0, 3
	s_bfm_b32 s0, s3, 0
	s_and_b32 s22, s0, s20
	s_lshl_b32 s0, s2, 6
	s_add_i32 s21, s21, s1
	s_ashr_i32 s1, s0, 31
	s_lshl_b64 s[24:25], s[0:1], 2
	v_lshl_add_u64 v[2:3], v[110:111], 0, s[24:25]
	global_load_dwordx4 v[84:87], v[2:3], off offset:16
	global_load_dwordx4 v[88:91], v[2:3], off
	s_waitcnt vmcnt(5)
	v_lshlrev_b32_e32 v102, 16, v8
	v_and_b32_e32 v103, 0xffff0000, v8
	v_lshlrev_b32_e32 v98, 16, v9
	v_and_b32_e32 v99, 0xffff0000, v9
	v_pk_mul_f32 v[104:105], v[102:103], v[102:103]
	v_pk_mul_f32 v[100:101], v[98:99], v[98:99]
	v_add_f32_e32 v1, v104, v105
	v_lshlrev_b32_e32 v94, 16, v10
	v_and_b32_e32 v95, 0xffff0000, v10
	v_add_f32_e32 v1, v100, v1
	v_pk_mul_f32 v[96:97], v[94:95], v[94:95]
	v_add_f32_e32 v1, v101, v1
	v_lshlrev_b32_e32 v2, 16, v11
	v_and_b32_e32 v3, 0xffff0000, v11
	v_add_f32_e32 v1, v96, v1
	v_pk_mul_f32 v[92:93], v[2:3], v[2:3]
	v_add_f32_e32 v1, v97, v1
	v_add_f32_e32 v1, v92, v1
	v_add_f32_e32 v1, v93, v1
	s_nop 1
	v_mov_b32_dpp v92, v1 quad_perm:[1,0,3,2] row_mask:0xf bank_mask:0xf
	v_lshlrev_b32_e32 v156, 16, v20
	v_and_b32_e32 v157, 0xffff0000, v20
	v_lshlrev_b32_e32 v152, 16, v21
	v_and_b32_e32 v153, 0xffff0000, v21
	s_waitcnt lgkmcnt(0)
	v_add_f32_e32 v1, v1, v92
	s_nop 1
	v_mov_b32_dpp v92, v1 quad_perm:[2,3,0,1] row_mask:0xf bank_mask:0xf
	v_pk_mul_f32 v[158:159], v[156:157], v[156:157]
	v_pk_mul_f32 v[154:155], v[152:153], v[152:153]
	v_mov_b32_e32 v162, v158
	v_lshlrev_b32_e32 v136, 16, v22
	s_waitcnt lgkmcnt(0)
	v_add_f32_e32 v1, v1, v92
	s_nop 1
	v_mov_b32_dpp v92, v1 row_half_mirror row_mask:0xf bank_mask:0xf
	v_and_b32_e32 v137, 0xffff0000, v22
	v_mov_b32_e32 v158, v154
	v_pk_mul_f32 v[150:151], v[136:137], v[136:137]
	v_lshlrev_b32_e32 v106, 16, v23
	s_waitcnt lgkmcnt(0)
	v_add_f32_e32 v1, v1, v92
	v_fmamk_f32 v1, v1, 0x3c800000, v139
	v_and_b32_e32 v107, 0xffff0000, v23
	v_rsq_f32_e32 v1, v1
	v_pk_mul_f32 v[134:135], v[106:107], v[106:107]
	s_mov_b32 s0, 0x358637bd
	s_mov_b32 s26, 0x3c800000
	s_nop 0
	v_mov_b32_e32 v96, v1
	v_pk_mul_f32 v[92:93], v[96:97], v[102:103] op_sel_hi:[0,1]
	v_pk_mul_f32 v[98:99], v[96:97], v[98:99] op_sel_hi:[0,1]
	v_pk_mul_f32 v[94:95], v[96:97], v[94:95] op_sel_hi:[0,1]
	v_pk_mul_f32 v[2:3], v[96:97], v[2:3] op_sel_hi:[0,1]
	v_lshlrev_b32_e32 v102, 16, v4
	v_and_b32_e32 v103, 0xffff0000, v4
	v_pk_mul_f32 v[104:105], v[102:103], v[102:103]
	s_waitcnt vmcnt(3)
	v_and_b32_e32 v179, 0xffff0000, v48
	v_mov_b32_e32 v163, v104
	v_mov_b32_e32 v104, v159
	v_pk_add_f32 v[104:105], v[162:163], v[104:105]
	v_lshlrev_b32_e32 v178, 16, v48
	v_mul_f32_e32 v240, v179, v179
	v_lshlrev_b32_e32 v176, 16, v49
	v_and_b32_e32 v177, 0xffff0000, v49
	v_pk_fma_f32 v[240:241], v[178:179], v[178:179], v[240:241] op_sel_hi:[1,1,0]
	v_mul_f32_e32 v242, v177, v177
	v_pk_fma_f32 v[240:241], v[176:177], v[176:177], v[240:241]
	v_lshlrev_b32_e32 v174, 16, v50
	v_and_b32_e32 v175, 0xffff0000, v50
	v_pk_add_f32 v[240:241], v[242:243], v[240:241] op_sel_hi:[0,1]
	v_pk_fma_f32 v[240:241], v[174:175], v[174:175], v[240:241]
	v_mul_f32_e32 v242, v175, v175
	v_lshlrev_b32_e32 v172, 16, v51
	v_and_b32_e32 v173, 0xffff0000, v51
	v_pk_add_f32 v[240:241], v[242:243], v[240:241] op_sel_hi:[0,1]
	v_add_u32_e32 v231, v113, v188
	v_lshlrev_b32_e32 v162, 16, v40
	v_and_b32_e32 v163, 0xffff0000, v40
	s_waitcnt vmcnt(2)
	v_lshlrev_b32_e32 v170, 16, v52
	s_waitcnt vmcnt(1)
	v_pk_mul_f32 v[94:95], v[84:85], v[94:95]
	s_waitcnt vmcnt(0)
	v_pk_mul_f32 v[92:93], v[88:89], v[92:93]
	v_pk_mul_f32 v[98:99], v[90:91], v[98:99]
	v_cvt_pk_bf16_f32 v92, v92, v93
	v_cvt_pk_bf16_f32 v93, v98, v99
	v_pk_mul_f32 v[2:3], v[86:87], v[2:3]
	v_lshlrev_b32_e32 v98, 16, v5
	v_and_b32_e32 v99, 0xffff0000, v5
	v_cvt_pk_bf16_f32 v94, v94, v95
	v_cvt_pk_bf16_f32 v95, v2, v3
	v_pk_mul_f32 v[100:101], v[98:99], v[98:99]
	ds_write_b128 v229, v[92:95]
	v_lshlrev_b32_e32 v94, 16, v6
	v_and_b32_e32 v95, 0xffff0000, v6
	v_mov_b32_e32 v159, v100
	v_pk_mul_f32 v[96:97], v[94:95], v[94:95]
	v_pk_add_f32 v[104:105], v[158:159], v[104:105]
	v_mov_b32_e32 v100, v155
	v_lshlrev_b32_e32 v2, 16, v7
	v_and_b32_e32 v3, 0xffff0000, v7
	v_pk_add_f32 v[100:101], v[100:101], v[104:105]
	v_mov_b32_e32 v104, v150
	v_mov_b32_e32 v105, v96
	v_pk_mul_f32 v[92:93], v[2:3], v[2:3]
	v_pk_add_f32 v[100:101], v[104:105], v[100:101]
	v_mov_b32_e32 v96, v151
	v_pk_add_f32 v[96:97], v[96:97], v[100:101]
	v_mov_b32_e32 v100, v134
	v_mov_b32_e32 v101, v92
	v_pk_add_f32 v[96:97], v[100:101], v[96:97]
	v_mov_b32_e32 v92, v135
	v_pk_add_f32 v[92:93], v[92:93], v[96:97]
	s_nop 1
	v_mov_b32_dpp v97, v93 quad_perm:[1,0,3,2] row_mask:0xf bank_mask:0xf
	s_nop 1
	v_mov_b32_dpp v96, v92 quad_perm:[1,0,3,2] row_mask:0xf bank_mask:0xf
	v_mov_b64_e32 v[134:135], s[0:1]
	v_and_b32_e32 v171, 0xffff0000, v52
	v_pk_fma_f32 v[240:241], v[172:173], v[172:173], v[240:241]
	v_mul_f32_e32 v242, v173, v173
	s_waitcnt lgkmcnt(0)
	v_pk_add_f32 v[92:93], v[92:93], v[96:97]
	s_nop 1
	v_mov_b32_dpp v97, v93 quad_perm:[2,3,0,1] row_mask:0xf bank_mask:0xf
	s_nop 1
	v_mov_b32_dpp v96, v92 quad_perm:[2,3,0,1] row_mask:0xf bank_mask:0xf
	ds_write_b128 v231, v[12:15] offset:36864
	v_pk_mul_f32 v[180:181], v[162:163], v[162:163]
	v_pk_mul_f32 v[238:239], v[170:171], v[170:171]
	v_pk_add_f32 v[240:241], v[242:243], v[240:241] op_sel_hi:[0,1]
	s_waitcnt lgkmcnt(1)
; #define LAS __attribute__((address_space(3)))
; __device__ __forceinline__ void attn_phase(LAS unsigned char* lds, const bf16* PROJ, const bf16* Ygate, bf16* OG0, bf16* OG1, bf16* OG2, float* LSE, const float* qnw, const float* knw, int bx, int G) {
;     ...
;             for (int jj = 0; jj < 4; ++jj) {
;                 const int key = (tid >> 3) + 64 * jj; const v4u kq = kr[half][jj];
;                 float kf[8] = {bflo(kq.x), bfhi(kq.x), bflo(kq.y), bfhi(kq.y), bflo(kq.z), bfhi(kq.z), bflo(kq.w), bfhi(kq.w)};
;                 float ss = 0.f;
; #pragma unroll
;                 for (int e = 0; e < 8; ++e) ss += kf[e] * kf[e];
;                 ss += __shfl_xor(ss, 1); ss += __shfl_xor(ss, 2); ss += __shfl_xor(ss, 4);
;                 const float rs = rsqrtf(ss * (1.f / 64.f) + EPS);
;                 v4u ko; ko.x = pk2(kf[0] * rs * kw0[0], kf[1] * rs * kw0[1]); ko.y = pk2(kf[2] * rs * kw0[2], kf[3] * rs * kw0[3]);
;                 ko.z = pk2(kf[4] * rs * kw1[0], kf[5] * rs * kw1[1]); ko.w = pk2(kf[6] * rs * kw1[2], kf[7] * rs * kw1[3]);
;                 *(LAS v4u*)(Ks + key * 72 + 8 * oct) = ko;
;                 *(LAS v4u*)(Vs + key * 80 + 8 * oct) = vr[half][jj];
;             }
;         }
;         const int qi = 16 * w + l16;
;         const size_t qrow = (size_t)bl * SEQL + (size_t)(128 * n + qi) * d + r;
;         bf16x8 qreg[2];
;         {
;             float qf[2][8]; float ss = 0.f;
; #pragma unroll
;             for (int ks = 0; ks < 2; ++ks) {
;                 const v4u qq = qr[half][ks];
;                 qf[ks][0] = bflo(qq.x); qf[ks][1] = bfhi(qq.x); qf[ks][2] = bflo(qq.y); qf[ks][3] = bfhi(qq.y); qf[ks][4] = bflo(qq.z); qf[ks][5] = bfhi(qq.z); qf[ks][6] = bflo(qq.w); qf[ks][7] = bfhi(qq.w);
; #pragma unroll
;                 for (int e = 0; e < 8; ++e) ss += qf[ks][e] * qf[ks][e];
;             }
;             ss += __shfl_xor(ss, 16); ss += __shfl_xor(ss, 32);
;             const float rs = rsqrtf(ss * (1.f / 64.f) + EPS) * 0.125f;
; #pragma unroll
;             for (int ks = 0; ks < 2; ++ks) {
;                 const f32x4 w0 = *(const f32x4*)(qnw + gi * 64 + 32 * ks + 8 * g4), w1 = *(const f32x4*)(qnw + gi * 64 + 32 * ks + 8 * g4 + 4);
;                 v4u tq; tq.x = pk2(qf[ks][0] * rs * w0[0], qf[ks][1] * rs * w0[1]); tq.y = pk2(qf[ks][2] * rs * w0[2], qf[ks][3] * rs * w0[3]);
	v_pk_add_f32 v[92:93], v[92:93], v[96:97]
	s_nop 1
	v_mov_b32_dpp v97, v93 row_half_mirror row_mask:0xf bank_mask:0xf
	s_nop 1
	v_mov_b32_dpp v96, v92 row_half_mirror row_mask:0xf bank_mask:0xf
	v_lshlrev_b32_e32 v168, 16, v53
	v_and_b32_e32 v169, 0xffff0000, v53
	v_mov_b32_e32 v242, v238
	v_mov_b32_e32 v243, v180
	s_waitcnt lgkmcnt(0)
	v_pk_add_f32 v[92:93], v[92:93], v[96:97]
	v_mov_b32_e32 v241, v181
	v_pk_fma_f32 v[96:97], v[92:93], s[26:27], v[134:135] op_sel_hi:[1,0,0]
	v_pk_mul_f32 v[236:237], v[168:169], v[168:169]
	v_pk_add_f32 v[180:181], v[242:243], v[240:241]
	v_mov_b32_e32 v1, v97
	v_rsq_f32_e32 v1, v1
	v_lshlrev_b32_e32 v166, 16, v54
	v_and_b32_e32 v167, 0xffff0000, v54
	v_pk_mul_f32 v[234:235], v[166:167], v[166:167]
	s_nop 0
	v_mov_b32_e32 v100, v1
	v_mov_b32_e32 v1, v96
	v_rsq_f32_e32 v1, v1
	v_pk_mul_f32 v[94:95], v[100:101], v[94:95] op_sel_hi:[0,1]
	v_pk_mul_f32 v[2:3], v[100:101], v[2:3] op_sel_hi:[0,1]
	v_pk_mul_f32 v[92:93], v[100:101], v[102:103] op_sel_hi:[0,1]
	v_pk_mul_f32 v[98:99], v[100:101], v[98:99] op_sel_hi:[0,1]
	v_pk_mul_f32 v[94:95], v[84:85], v[94:95]
	v_pk_mul_f32 v[2:3], v[86:87], v[2:3]
	v_pk_mul_f32 v[92:93], v[88:89], v[92:93]
	v_pk_mul_f32 v[98:99], v[90:91], v[98:99]
	v_cvt_pk_bf16_f32 v94, v94, v95
	v_cvt_pk_bf16_f32 v95, v2, v3
	s_nop 0
	v_cvt_pk_bf16_f32 v92, v92, v93
	v_cvt_pk_bf16_f32 v93, v98, v99
	v_mov_b32_e32 v2, v1
	ds_write_b128 v229, v[92:95] offset:9216
	ds_write_b128 v231, v[16:19] offset:47104
	v_pk_mul_f32 v[92:93], v[2:3], v[156:157] op_sel_hi:[0,1]
	v_lshlrev_b32_e32 v156, 16, v41
	v_and_b32_e32 v157, 0xffff0000, v41
	v_pk_mul_f32 v[158:159], v[156:157], v[156:157]
	v_pk_mul_f32 v[94:95], v[2:3], v[152:153] op_sel_hi:[0,1]
	v_lshlrev_b32_e32 v152, 16, v42
	v_and_b32_e32 v153, 0xffff0000, v42
	v_pk_mov_b32 v[238:239], v[238:239], v[158:159] op_sel:[1,0]
	v_pk_mul_f32 v[92:93], v[88:89], v[92:93]
	v_pk_mul_f32 v[94:95], v[90:91], v[94:95]
	v_pk_mul_f32 v[154:155], v[152:153], v[152:153]
	v_pk_add_f32 v[180:181], v[238:239], v[180:181]
	v_mov_b32_e32 v158, v236
	v_cvt_pk_bf16_f32 v92, v92, v93
	v_cvt_pk_bf16_f32 v93, v94, v95
	v_pk_mul_f32 v[94:95], v[2:3], v[136:137] op_sel_hi:[0,1]
	v_lshlrev_b32_e32 v136, 16, v43
	v_and_b32_e32 v137, 0xffff0000, v43
	v_pk_add_f32 v[158:159], v[158:159], v[180:181]
	v_pk_mov_b32 v[180:181], v[236:237], v[154:155] op_sel:[1,0]
	v_pk_mul_f32 v[150:151], v[136:137], v[136:137]
	v_lshlrev_b32_e32 v164, 16, v55
	v_and_b32_e32 v165, 0xffff0000, v55
	v_pk_add_f32 v[158:159], v[180:181], v[158:159]
	v_mov_b32_e32 v154, v234
	v_pk_mul_f32 v[232:233], v[164:165], v[164:165]
	v_pk_add_f32 v[154:155], v[154:155], v[158:159]
	v_pk_mov_b32 v[158:159], v[234:235], v[150:151] op_sel:[1,0]
	v_mov_b32_e32 v150, v232
	v_pk_add_f32 v[154:155], v[158:159], v[154:155]
	v_pk_mul_f32 v[2:3], v[2:3], v[106:107] op_sel_hi:[0,1]
	v_pk_add_f32 v[150:151], v[150:151], v[154:155]
	s_nop 1
	v_mov_b32_dpp v155, v151 quad_perm:[1,0,3,2] row_mask:0xf bank_mask:0xf
	v_mov_b32_e32 v154, v233
	v_pk_mul_f32 v[94:95], v[84:85], v[94:95]
	v_pk_mul_f32 v[2:3], v[86:87], v[2:3]
	s_ashr_i32 s0, s21, 4
	s_waitcnt lgkmcnt(0)
	v_pk_add_f32 v[150:151], v[154:155], v[150:151]
	s_nop 1
	v_mov_b32_dpp v155, v151 quad_perm:[2,3,0,1] row_mask:0xf bank_mask:0xf
	v_mov_b32_e32 v154, v150
	s_nop 1
	v_permlane16_swap_b32_e32 v154, v150
	s_lshr_b32 s54, s20, s3
	v_cvt_pk_bf16_f32 v94, v94, v95
	v_cvt_pk_bf16_f32 v95, v2, v3
	s_ashr_i32 s1, s0, 31
	s_waitcnt lgkmcnt(0)
	v_pk_add_f32 v[150:151], v[150:151], v[154:155]
	s_nop 1
	v_mov_b32_dpp v155, v151 row_half_mirror row_mask:0xf bank_mask:0xf
	v_mov_b32_e32 v154, v150
	s_nop 1
	v_permlane32_swap_b32_e32 v154, v150
	v_lshl_add_u32 v2, s54, 7, v147
	s_and_b32 s53, s21, 15
	s_lshl_b64 s[20:21], s[0:1], 11
	v_ashrrev_i32_e32 v3, 31, v2
	s_waitcnt lgkmcnt(0)
	v_pk_add_f32 v[150:151], v[150:151], v[154:155]
	s_or_b32 s20, s20, s22
	v_pk_fma_f32 v[180:181], v[150:151], s[26:27], v[134:135] op_sel_hi:[1,0,0]
	v_lshlrev_b64 v[2:3], s3, v[2:3]
	ds_write_b128 v229, v[92:95] offset:18432
	ds_write_b128 v231, v[24:27] offset:57344
	v_mov_b32_e32 v1, v181
	v_rsq_f32_e32 v1, v1
	v_lshl_add_u64 v[96:97], v[114:115], 0, s[24:25]
	s_lshl_b32 s26, s53, 7
	global_load_dwordx4 v[100:103], v[96:97], off offset:16
	global_load_dwordx4 v[104:107], v[96:97], off
	global_load_dwordx4 v[92:95], v[96:97], off offset:144
	s_nop 0
	global_load_dwordx4 v[96:99], v[96:97], off offset:128
	s_nop 0
	v_mov_b32_e32 v134, v1
	v_pk_mul_f32 v[150:151], v[134:135], v[162:163] op_sel_hi:[0,1]
	v_pk_mul_f32 v[88:89], v[88:89], v[150:151]
	v_pk_mul_f32 v[150:151], v[134:135], v[156:157] op_sel_hi:[0,1]
	v_pk_mul_f32 v[90:91], v[90:91], v[150:151]
	v_cvt_pk_bf16_f32 v88, v88, v89
	v_cvt_pk_bf16_f32 v89, v90, v91
	v_pk_mul_f32 v[90:91], v[134:135], v[152:153] op_sel_hi:[0,1]
	v_pk_mul_f32 v[84:85], v[84:85], v[90:91]
	v_cmp_gt_f32_e64 s[0:1], s33, v180
	v_cvt_pk_bf16_f32 v90, v84, v85
	v_pk_mul_f32 v[84:85], v[134:135], v[136:137] op_sel_hi:[0,1]
	v_lshl_add_u64 v[136:137], s[20:21], 0, v[2:3]
	v_lshlrev_b64 v[162:163], 11, v[136:137]
	v_pk_mul_f32 v[84:85], v[86:87], v[84:85]
	v_lshl_add_u64 v[2:3], s[28:29], 0, v[162:163]
	v_cvt_pk_bf16_f32 v91, v84, v85
	v_lshl_add_u64 v[2:3], v[2:3], 0, s[26:27]
	v_lshlrev_b32_e32 v134, 1, v112
	v_mov_b32_e32 v135, v0
	ds_write_b128 v229, v[88:91] offset:27648
	ds_write_b128 v230, v[44:47] offset:57344
	v_lshl_add_u64 v[2:3], v[2:3], 0, v[134:135]
	global_load_dwordx4 v[88:91], v[2:3], off
	global_load_dwordx4 v[84:87], v[2:3], off offset:64
	v_readlane_b32 s20, v252, 59
	s_add_i32 s52, s51, s20
	s_waitcnt lgkmcnt(0)
	s_barrier
; __device__ __forceinline__ void attn_phase(LAS unsigned char* lds, const bf16* PROJ, const bf16* Ygate, bf16* OG0, bf16* OG1, bf16* OG2, float* LSE, const float* qnw, const float* knw, int bx, int G) {
;     ...
;         if (t + 2 * G < 3072) AT_LOAD(t + 2 * G, half);
	s_cmpk_gt_i32 s52, 0xbff
	s_cselect_b64 s[24:25], -1, 0
	s_and_b64 vcc, exec, s[24:25]
	s_cbranch_vccnz .LBB0_279
	s_ashr_i32 s21, s52, 4
	s_mul_hi_i32 s22, s21, 0x55555556
	s_lshr_b32 s23, s22, 31
	s_add_i32 s22, s22, s23
	s_mul_i32 s22, s22, 3
	s_sub_i32 s21, s21, s22
	s_mul_hi_i32 s22, s52, 0x2aaaaaab
	s_lshr_b32 s23, s22, 31
	s_ashr_i32 s22, s22, 3
	s_lshl_b32 s26, s21, 1
	s_and_b32 s20, s52, 15
	s_add_i32 s23, s22, s23
	s_lshl_b32 s30, -1, s26
	s_andn2_b32 s30, s20, s30
	s_lshr_b32 s31, s20, s26
	s_lshl_b32 s20, s23, 6
	s_ashr_i32 s22, s23, 4
	s_mulk_i32 s21, 0xc00
	s_and_b32 s20, s20, 0x3c0
	s_or_b32 s20, s21, s20
	s_ashr_i32 s23, s22, 31
	s_lshl_b64 s[22:23], s[22:23], 11
	s_ashr_i32 s21, s20, 31
	s_lshl_b32 s55, s31, 7
	s_or_b32 s22, s22, s30
	s_lshl_b64 s[30:31], s[20:21], 1
	v_mov_b32_e32 v6, v0
	v_mov_b32_e32 v7, v0
	v_add_u32_e32 v48, s55, v182
	s_add_u32 s38, s34, s30
	v_mov_b32_e32 v4, v0
	v_mov_b32_e32 v5, v0
	v_mov_b64_e32 v[10:11], v[6:7]
	v_mov_b64_e32 v[14:15], v[6:7]
	s_addc_u32 s39, s35, s31
	v_cmp_lt_i32_e32 vcc, -1, v48
	v_mov_b64_e32 v[8:9], v[4:5]
	v_mov_b64_e32 v[12:13], v[4:5]
	s_and_saveexec_b64 s[30:31], vcc
	s_cbranch_execz .LBB0_272
	v_mov_b32_e32 v49, v0
	v_lshlrev_b64 v[2:3], s26, v[48:49]
	v_lshl_add_u64 v[2:3], v[2:3], 0, s[22:23]
	v_mov_b64_e32 v[8:9], s[38:39]
	s_movk_i32 s80, 0x4800
	v_mad_u64_u32 v[8:9], vcc, v2, s80, v[8:9]
	v_mov_b32_e32 v2, v9
	v_mad_u64_u32 v[2:3], vcc, v3, s80, v[2:3]
	v_mov_b32_e32 v9, v2
	v_lshlrev_b32_e32 v2, 1, v108
	v_mov_b32_e32 v3, v0
	v_lshl_add_u64 v[2:3], v[8:9], 0, v[2:3]
	v_add_co_u32_e32 v12, vcc, 0x1000, v2
	s_nop 1
	v_addc_co_u32_e32 v13, vcc, 0, v3, vcc
	global_load_dwordx4 v[8:11], v[2:3], off offset:2048
	s_nop 0
	global_load_dwordx4 v[12:15], v[12:13], off

; #define LAS __attribute__((address_space(3)))
; __device__ __forceinline__ float bflo(unsigned u) { return __uint_as_float(u << 16); }
; __device__ __forceinline__ float bfhi(unsigned u) { return __uint_as_float(u & 0xffff0000u); }
; __device__ __forceinline__ unsigned pk2(float lo, float hi) { f32x2_t v = {lo, hi}; bf16x2_t b = __builtin_convertvector(v, bf16x2_t); return __builtin_bit_cast(unsigned, b); }
; __device__ __forceinline__ void attn_phase(LAS unsigned char* lds, const bf16* PROJ, const bf16* Ygate, bf16* OG0, bf16* OG1, bf16* OG2, float* LSE, const float* qnw, const float* knw, int bx, int G) {
;     ...
;         const int sub = t & 15, gi = (t >> 4) % 3, bh = t / 48, h = bh & 15, bl = bh >> 4;
;         const int sh = 2 * gi, d = 1 << sh, r = sub & (d - 1), n = sub >> sh;
;         const float ad = exp2f(-8.f * (float)(gi * 16 + h + 1) / 48.f) * (float)d;
;         bf16* OG = gi == 0 ? OG0 : (gi == 1 ? OG1 : OG2);
;         {
;             const f32x4 kw0 = *(const f32x4*)(knw + gi * 64 + 8 * oct), kw1 = *(const f32x4*)(knw + gi * 64 + 8 * oct + 4);
; #pragma unroll
;             for (int jj = 0; jj < 4; ++jj) {
;                 const int key = (tid >> 3) + 64 * jj; const v4u kq = kr[half][jj];
;                 float kf[8] = {bflo(kq.x), bfhi(kq.x), bflo(kq.y), bfhi(kq.y), bflo(kq.z), bfhi(kq.z), bflo(kq.w), bfhi(kq.w)};
;                 float ss = 0.f;
; #pragma unroll
;                 for (int e = 0; e < 8; ++e) ss += kf[e] * kf[e];
;                 ss += __shfl_xor(ss, 1); ss += __shfl_xor(ss, 2); ss += __shfl_xor(ss, 4);
;                 const float rs = rsqrtf(ss * (1.f / 64.f) + EPS);
;                 v4u ko; ko.x = pk2(kf[0] * rs * kw0[0], kf[1] * rs * kw0[1]); ko.y = pk2(kf[2] * rs * kw0[2], kf[3] * rs * kw0[3]);
;                 ko.z = pk2(kf[4] * rs * kw1[0], kf[5] * rs * kw1[1]); ko.w = pk2(kf[6] * rs * kw1[2], kf[7] * rs * kw1[3]);
;                 *(LAS v4u*)(Ks + key * 72 + 8 * oct) = ko;
;                 *(LAS v4u*)(Vs + key * 80 + 8 * oct) = vr[half][jj];
.LBB0_308:
	s_or_b64 exec, exec, s[0:1]
	s_waitcnt lgkmcnt(0)
	s_barrier
	s_add_i32 s0, s84, s51
	s_cmpk_gt_i32 s0, 0xbff
	s_cbranch_scc1 .LBB0_268
	s_ashr_i32 s1, s0, 4
	s_mul_hi_i32 s2, s1, 0x55555556
	s_lshr_b32 s3, s2, 31
	s_add_i32 s2, s2, s3
	s_mul_i32 s2, s2, 3
	s_sub_i32 s2, s1, s2
	s_and_b32 s22, s0, 15
	s_mul_hi_i32 s0, s0, 0x2aaaaaab
	s_lshl_b32 s3, s2, 1
	s_lshr_b32 s1, s0, 31
	s_ashr_i32 s23, s0, 3
	s_bfm_b32 s0, s3, 0
	s_and_b32 s26, s0, s22
	s_lshl_b32 s0, s2, 6
	s_add_i32 s23, s23, s1
	s_ashr_i32 s1, s0, 31
	s_lshl_b64 s[20:21], s[0:1], 2
	v_lshl_add_u64 v[2:3], v[110:111], 0, s[20:21]
	global_load_dwordx4 v[84:87], v[2:3], off offset:16
	global_load_dwordx4 v[88:91], v[2:3], off
	v_lshlrev_b32_e32 v102, 16, v32
	v_and_b32_e32 v103, 0xffff0000, v32
	v_lshlrev_b32_e32 v98, 16, v33
	v_and_b32_e32 v99, 0xffff0000, v33
	v_pk_mul_f32 v[104:105], v[102:103], v[102:103]
	v_pk_mul_f32 v[100:101], v[98:99], v[98:99]
	v_add_f32_e32 v1, v104, v105
	v_lshlrev_b32_e32 v94, 16, v34
	v_and_b32_e32 v95, 0xffff0000, v34
	v_add_f32_e32 v1, v100, v1
	v_pk_mul_f32 v[96:97], v[94:95], v[94:95]
	v_add_f32_e32 v1, v101, v1
	v_lshlrev_b32_e32 v2, 16, v35
	v_and_b32_e32 v3, 0xffff0000, v35
	v_add_f32_e32 v1, v96, v1
	v_pk_mul_f32 v[92:93], v[2:3], v[2:3]
	v_add_f32_e32 v1, v97, v1
	v_add_f32_e32 v1, v92, v1
	v_add_f32_e32 v1, v93, v1
	s_nop 1
	v_mov_b32_dpp v92, v1 quad_perm:[1,0,3,2] row_mask:0xf bank_mask:0xf
	v_lshlrev_b32_e32 v158, 16, v60
	v_and_b32_e32 v159, 0xffff0000, v60
	v_lshlrev_b32_e32 v154, 16, v61
	v_and_b32_e32 v155, 0xffff0000, v61
	s_waitcnt lgkmcnt(0)
	v_add_f32_e32 v1, v1, v92
	s_nop 1
	v_mov_b32_dpp v92, v1 quad_perm:[2,3,0,1] row_mask:0xf bank_mask:0xf
	v_pk_mul_f32 v[162:163], v[158:159], v[158:159]
	v_pk_mul_f32 v[156:157], v[154:155], v[154:155]
	v_mov_b32_e32 v164, v162
	v_lshlrev_b32_e32 v150, 16, v62
	s_waitcnt lgkmcnt(0)
	v_add_f32_e32 v1, v1, v92
	s_nop 1
	v_mov_b32_dpp v92, v1 row_half_mirror row_mask:0xf bank_mask:0xf
	v_and_b32_e32 v151, 0xffff0000, v62
	v_mov_b32_e32 v162, v156
	v_pk_mul_f32 v[152:153], v[150:151], v[150:151]
	v_lshlrev_b32_e32 v106, 16, v63
	s_waitcnt lgkmcnt(0)
	v_add_f32_e32 v1, v1, v92
	v_fmamk_f32 v1, v1, 0x3c800000, v139
	v_and_b32_e32 v107, 0xffff0000, v63
	v_rsq_f32_e32 v1, v1
	v_pk_mul_f32 v[136:137], v[106:107], v[106:107]
	s_mov_b32 s0, 0x358637bd
	s_mov_b32 s38, 0x3c800000
	s_nop 0
	v_mov_b32_e32 v96, v1
	v_pk_mul_f32 v[92:93], v[96:97], v[102:103] op_sel_hi:[0,1]
	v_pk_mul_f32 v[98:99], v[96:97], v[98:99] op_sel_hi:[0,1]
	v_pk_mul_f32 v[94:95], v[96:97], v[94:95] op_sel_hi:[0,1]
	v_pk_mul_f32 v[2:3], v[96:97], v[2:3] op_sel_hi:[0,1]
	v_lshlrev_b32_e32 v102, 16, v28
	v_and_b32_e32 v103, 0xffff0000, v28
	v_pk_mul_f32 v[104:105], v[102:103], v[102:103]
	v_and_b32_e32 v179, 0xffff0000, v76
	v_mov_b32_e32 v165, v104
	v_mov_b32_e32 v104, v163
	v_pk_add_f32 v[104:105], v[164:165], v[104:105]
	v_lshlrev_b32_e32 v178, 16, v76
	v_mul_f32_e32 v242, v179, v179
	v_lshlrev_b32_e32 v176, 16, v77
	v_and_b32_e32 v177, 0xffff0000, v77
	v_pk_fma_f32 v[242:243], v[178:179], v[178:179], v[242:243] op_sel_hi:[1,1,0]
	v_mul_f32_e32 v244, v177, v177
	v_pk_fma_f32 v[242:243], v[176:177], v[176:177], v[242:243]
	v_lshlrev_b32_e32 v174, 16, v78
	v_and_b32_e32 v175, 0xffff0000, v78
	v_pk_add_f32 v[242:243], v[244:245], v[242:243] op_sel_hi:[0,1]
	v_pk_fma_f32 v[242:243], v[174:175], v[174:175], v[242:243]
	v_mul_f32_e32 v244, v175, v175
	v_lshlrev_b32_e32 v172, 16, v79
	v_and_b32_e32 v173, 0xffff0000, v79
	v_pk_add_f32 v[242:243], v[244:245], v[242:243] op_sel_hi:[0,1]
	v_lshlrev_b32_e32 v232, 16, v68
	v_and_b32_e32 v233, 0xffff0000, v68
	v_lshlrev_b32_e32 v170, 16, v80
	v_and_b32_e32 v171, 0xffff0000, v80
	s_waitcnt vmcnt(1)
	v_pk_mul_f32 v[94:95], v[84:85], v[94:95]
	s_waitcnt vmcnt(0)
	v_pk_mul_f32 v[92:93], v[88:89], v[92:93]
	v_pk_mul_f32 v[98:99], v[90:91], v[98:99]
	v_cvt_pk_bf16_f32 v92, v92, v93
	v_cvt_pk_bf16_f32 v93, v98, v99
	v_pk_mul_f32 v[2:3], v[86:87], v[2:3]
	v_lshlrev_b32_e32 v98, 16, v29
	v_and_b32_e32 v99, 0xffff0000, v29
	v_cvt_pk_bf16_f32 v94, v94, v95
	v_cvt_pk_bf16_f32 v95, v2, v3
	v_pk_mul_f32 v[100:101], v[98:99], v[98:99]
	ds_write_b128 v229, v[92:95]
	ds_write_b128 v231, v[36:39] offset:36864
	v_lshlrev_b32_e32 v94, 16, v30
	v_and_b32_e32 v95, 0xffff0000, v30
	v_mov_b32_e32 v163, v100
	v_pk_mul_f32 v[96:97], v[94:95], v[94:95]
	v_pk_add_f32 v[104:105], v[162:163], v[104:105]
	v_mov_b32_e32 v100, v157
	v_lshlrev_b32_e32 v2, 16, v31
	v_and_b32_e32 v3, 0xffff0000, v31
	v_pk_add_f32 v[100:101], v[100:101], v[104:105]
	v_mov_b32_e32 v104, v152
	v_mov_b32_e32 v105, v96
	v_pk_mul_f32 v[92:93], v[2:3], v[2:3]
	v_pk_add_f32 v[100:101], v[104:105], v[100:101]
	v_mov_b32_e32 v96, v153
	v_pk_add_f32 v[96:97], v[96:97], v[100:101]
	v_mov_b32_e32 v100, v136
	v_mov_b32_e32 v101, v92
	v_pk_add_f32 v[96:97], v[100:101], v[96:97]
	v_mov_b32_e32 v92, v137
	v_pk_add_f32 v[92:93], v[92:93], v[96:97]
	s_nop 1
	v_mov_b32_dpp v97, v93 quad_perm:[1,0,3,2] row_mask:0xf bank_mask:0xf
	s_nop 1
	v_mov_b32_dpp v96, v92 quad_perm:[1,0,3,2] row_mask:0xf bank_mask:0xf
	v_mov_b64_e32 v[136:137], s[0:1]
	v_pk_fma_f32 v[242:243], v[172:173], v[172:173], v[242:243]
	v_mul_f32_e32 v244, v173, v173
	v_pk_mul_f32 v[180:181], v[232:233], v[232:233]
	s_waitcnt lgkmcnt(0)
	v_pk_add_f32 v[92:93], v[92:93], v[96:97]
	s_nop 1
	v_mov_b32_dpp v97, v93 quad_perm:[2,3,0,1] row_mask:0xf bank_mask:0xf
	s_nop 1
	v_mov_b32_dpp v96, v92 quad_perm:[2,3,0,1] row_mask:0xf bank_mask:0xf
	v_pk_mul_f32 v[240:241], v[170:171], v[170:171]
	v_pk_add_f32 v[242:243], v[244:245], v[242:243] op_sel_hi:[0,1]
	v_lshlrev_b32_e32 v168, 16, v81
	v_and_b32_e32 v169, 0xffff0000, v81
	s_waitcnt lgkmcnt(0)
; #define LAS __attribute__((address_space(3)))
; __device__ __forceinline__ void attn_phase(LAS unsigned char* lds, const bf16* PROJ, const bf16* Ygate, bf16* OG0, bf16* OG1, bf16* OG2, float* LSE, const float* qnw, const float* knw, int bx, int G) {
;     ...
;             for (int jj = 0; jj < 4; ++jj) {
;                 const int key = (tid >> 3) + 64 * jj; const v4u kq = kr[half][jj];
;                 float kf[8] = {bflo(kq.x), bfhi(kq.x), bflo(kq.y), bfhi(kq.y), bflo(kq.z), bfhi(kq.z), bflo(kq.w), bfhi(kq.w)};
;                 float ss = 0.f;
; #pragma unroll
;                 for (int e = 0; e < 8; ++e) ss += kf[e] * kf[e];
;                 ss += __shfl_xor(ss, 1); ss += __shfl_xor(ss, 2); ss += __shfl_xor(ss, 4);
;                 const float rs = rsqrtf(ss * (1.f / 64.f) + EPS);
;                 v4u ko; ko.x = pk2(kf[0] * rs * kw0[0], kf[1] * rs * kw0[1]); ko.y = pk2(kf[2] * rs * kw0[2], kf[3] * rs * kw0[3]);
;                 ko.z = pk2(kf[4] * rs * kw1[0], kf[5] * rs * kw1[1]); ko.w = pk2(kf[6] * rs * kw1[2], kf[7] * rs * kw1[3]);
;                 *(LAS v4u*)(Ks + key * 72 + 8 * oct) = ko;
;                 *(LAS v4u*)(Vs + key * 80 + 8 * oct) = vr[half][jj];
;             }
;         }
;         const int qi = 16 * w + l16;
;         const size_t qrow = (size_t)bl * SEQL + (size_t)(128 * n + qi) * d + r;
;         bf16x8 qreg[2];
;         {
;             float qf[2][8]; float ss = 0.f;
; #pragma unroll
;             for (int ks = 0; ks < 2; ++ks) {
;                 const v4u qq = qr[half][ks];
;                 qf[ks][0] = bflo(qq.x); qf[ks][1] = bfhi(qq.x); qf[ks][2] = bflo(qq.y); qf[ks][3] = bfhi(qq.y); qf[ks][4] = bflo(qq.z); qf[ks][5] = bfhi(qq.z); qf[ks][6] = bflo(qq.w); qf[ks][7] = bfhi(qq.w);
; #pragma unroll
;                 for (int e = 0; e < 8; ++e) ss += qf[ks][e] * qf[ks][e];
;             }
;             ss += __shfl_xor(ss, 16); ss += __shfl_xor(ss, 32);
;             const float rs = rsqrtf(ss * (1.f / 64.f) + EPS) * 0.125f;
; #pragma unroll
;             for (int ks = 0; ks < 2; ++ks) {
;                 const f32x4 w0 = *(const f32x4*)(qnw + gi * 64 + 32 * ks + 8 * g4), w1 = *(const f32x4*)(qnw + gi * 64 + 32 * ks + 8 * g4 + 4);
;                 v4u tq; tq.x = pk2(qf[ks][0] * rs * w0[0], qf[ks][1] * rs * w0[1]); tq.y = pk2(qf[ks][2] * rs * w0[2], qf[ks][3] * rs * w0[3]);
	v_pk_add_f32 v[92:93], v[92:93], v[96:97]
	s_nop 1
	v_mov_b32_dpp v97, v93 row_half_mirror row_mask:0xf bank_mask:0xf
	s_nop 1
	v_mov_b32_dpp v96, v92 row_half_mirror row_mask:0xf bank_mask:0xf
	v_mov_b32_e32 v244, v240
	v_mov_b32_e32 v245, v180
	v_mov_b32_e32 v243, v181
	v_pk_mul_f32 v[238:239], v[168:169], v[168:169]
	s_waitcnt lgkmcnt(0)
	v_pk_add_f32 v[92:93], v[92:93], v[96:97]
	v_pk_add_f32 v[180:181], v[244:245], v[242:243]
	v_pk_fma_f32 v[96:97], v[92:93], s[38:39], v[136:137] op_sel_hi:[1,0,0]
	v_lshlrev_b32_e32 v166, 16, v82
	v_and_b32_e32 v167, 0xffff0000, v82
	v_mov_b32_e32 v1, v97
	v_rsq_f32_e32 v1, v1
	v_pk_mul_f32 v[236:237], v[166:167], v[166:167]
	v_lshlrev_b32_e32 v164, 16, v83
	v_and_b32_e32 v165, 0xffff0000, v83
	s_nop 0
	v_mov_b32_e32 v100, v1
	v_mov_b32_e32 v1, v96
	v_rsq_f32_e32 v1, v1
	v_pk_mul_f32 v[94:95], v[100:101], v[94:95] op_sel_hi:[0,1]
	v_pk_mul_f32 v[2:3], v[100:101], v[2:3] op_sel_hi:[0,1]
	v_pk_mul_f32 v[92:93], v[100:101], v[102:103] op_sel_hi:[0,1]
	v_pk_mul_f32 v[98:99], v[100:101], v[98:99] op_sel_hi:[0,1]
	v_pk_mul_f32 v[94:95], v[84:85], v[94:95]
	v_pk_mul_f32 v[2:3], v[86:87], v[2:3]
	v_pk_mul_f32 v[92:93], v[88:89], v[92:93]
	v_pk_mul_f32 v[98:99], v[90:91], v[98:99]
	v_cvt_pk_bf16_f32 v94, v94, v95
	v_cvt_pk_bf16_f32 v95, v2, v3
	s_nop 0
	v_cvt_pk_bf16_f32 v92, v92, v93
	v_cvt_pk_bf16_f32 v93, v98, v99
	v_mov_b32_e32 v2, v1
	ds_write_b128 v229, v[92:95] offset:9216
	ds_write_b128 v231, v[56:59] offset:47104
	v_pk_mul_f32 v[92:93], v[2:3], v[158:159] op_sel_hi:[0,1]
	v_lshlrev_b32_e32 v158, 16, v69
	v_and_b32_e32 v159, 0xffff0000, v69
	v_pk_mul_f32 v[162:163], v[158:159], v[158:159]
	v_pk_mul_f32 v[94:95], v[2:3], v[154:155] op_sel_hi:[0,1]
	v_lshlrev_b32_e32 v154, 16, v70
	v_and_b32_e32 v155, 0xffff0000, v70
	v_pk_mov_b32 v[240:241], v[240:241], v[162:163] op_sel:[1,0]
	v_pk_mul_f32 v[92:93], v[88:89], v[92:93]
	v_pk_mul_f32 v[94:95], v[90:91], v[94:95]
	v_pk_mul_f32 v[156:157], v[154:155], v[154:155]
	v_pk_add_f32 v[180:181], v[240:241], v[180:181]
	v_mov_b32_e32 v162, v238
	v_cvt_pk_bf16_f32 v92, v92, v93
	v_cvt_pk_bf16_f32 v93, v94, v95
	v_pk_mul_f32 v[94:95], v[2:3], v[150:151] op_sel_hi:[0,1]
	v_lshlrev_b32_e32 v150, 16, v71
	v_and_b32_e32 v151, 0xffff0000, v71
	v_pk_add_f32 v[162:163], v[162:163], v[180:181]
	v_pk_mov_b32 v[180:181], v[238:239], v[156:157] op_sel:[1,0]
	v_pk_mul_f32 v[152:153], v[150:151], v[150:151]
	v_pk_add_f32 v[162:163], v[180:181], v[162:163]
	v_mov_b32_e32 v156, v236
	v_pk_mul_f32 v[234:235], v[164:165], v[164:165]
	v_pk_add_f32 v[156:157], v[156:157], v[162:163]
	v_pk_mov_b32 v[162:163], v[236:237], v[152:153] op_sel:[1,0]
	v_mov_b32_e32 v152, v234
	v_pk_add_f32 v[156:157], v[162:163], v[156:157]
	v_pk_mul_f32 v[2:3], v[2:3], v[106:107] op_sel_hi:[0,1]
	v_pk_add_f32 v[152:153], v[152:153], v[156:157]
	s_nop 1
	v_mov_b32_dpp v157, v153 quad_perm:[1,0,3,2] row_mask:0xf bank_mask:0xf
	v_mov_b32_e32 v156, v235
	v_pk_mul_f32 v[94:95], v[84:85], v[94:95]
	v_pk_mul_f32 v[2:3], v[86:87], v[2:3]
	s_ashr_i32 s0, s23, 4
	s_waitcnt lgkmcnt(0)
	v_pk_add_f32 v[152:153], v[156:157], v[152:153]
	s_nop 1
	v_mov_b32_dpp v157, v153 quad_perm:[2,3,0,1] row_mask:0xf bank_mask:0xf
	v_mov_b32_e32 v156, v152
	s_nop 1
	v_permlane16_swap_b32_e32 v156, v152
	s_lshr_b32 s54, s22, s3
	v_cvt_pk_bf16_f32 v94, v94, v95
	v_cvt_pk_bf16_f32 v95, v2, v3
	s_ashr_i32 s1, s0, 31
	s_waitcnt lgkmcnt(0)
	v_pk_add_f32 v[152:153], v[152:153], v[156:157]
	s_nop 1
	v_mov_b32_dpp v157, v153 row_half_mirror row_mask:0xf bank_mask:0xf
	v_mov_b32_e32 v156, v152
	s_nop 1
	v_permlane32_swap_b32_e32 v156, v152
	v_lshl_add_u32 v2, s54, 7, v147
	s_and_b32 s53, s23, 15
	s_lshl_b64 s[22:23], s[0:1], 11
	v_ashrrev_i32_e32 v3, 31, v2
	s_waitcnt lgkmcnt(0)
	v_pk_add_f32 v[152:153], v[152:153], v[156:157]
	s_or_b32 s22, s22, s26
	v_pk_fma_f32 v[180:181], v[152:153], s[38:39], v[136:137] op_sel_hi:[1,0,0]
	v_lshlrev_b64 v[2:3], s3, v[2:3]
	ds_write_b128 v229, v[92:95] offset:18432
	ds_write_b128 v231, v[64:67] offset:57344
	v_mov_b32_e32 v1, v181
	v_rsq_f32_e32 v1, v1
	v_lshl_add_u64 v[96:97], v[114:115], 0, s[20:21]
	s_lshl_b32 s26, s53, 7
	global_load_dwordx4 v[100:103], v[96:97], off offset:16
	global_load_dwordx4 v[104:107], v[96:97], off
	global_load_dwordx4 v[92:95], v[96:97], off offset:144
	s_nop 0
	global_load_dwordx4 v[96:99], v[96:97], off offset:128
	s_nop 0
	v_mov_b32_e32 v136, v1
	v_pk_mul_f32 v[152:153], v[136:137], v[232:233] op_sel_hi:[0,1]
	v_pk_mul_f32 v[88:89], v[88:89], v[152:153]
	v_pk_mul_f32 v[152:153], v[136:137], v[158:159] op_sel_hi:[0,1]
	v_pk_mul_f32 v[90:91], v[90:91], v[152:153]
	v_cvt_pk_bf16_f32 v88, v88, v89
	v_cvt_pk_bf16_f32 v89, v90, v91
	v_pk_mul_f32 v[90:91], v[136:137], v[154:155] op_sel_hi:[0,1]
	v_pk_mul_f32 v[84:85], v[84:85], v[90:91]
	v_mov_b32_e32 v135, v0
	v_cvt_pk_bf16_f32 v90, v84, v85
	v_pk_mul_f32 v[84:85], v[136:137], v[150:151] op_sel_hi:[0,1]
	v_lshl_add_u64 v[136:137], s[22:23], 0, v[2:3]
	v_lshlrev_b64 v[162:163], 11, v[136:137]
	v_pk_mul_f32 v[84:85], v[86:87], v[84:85]
	v_lshl_add_u64 v[2:3], s[28:29], 0, v[162:163]
	v_cvt_pk_bf16_f32 v91, v84, v85
	v_lshl_add_u64 v[2:3], v[2:3], 0, s[26:27]
	ds_write_b128 v229, v[88:91] offset:27648
	ds_write_b128 v230, v[72:75] offset:57344
	v_lshl_add_u64 v[2:3], v[2:3], 0, v[134:135]
	global_load_dwordx4 v[88:91], v[2:3], off
	global_load_dwordx4 v[84:87], v[2:3], off offset:64
	s_waitcnt lgkmcnt(0)
	s_barrier
; __device__ __forceinline__ void attn_phase(LAS unsigned char* lds, const bf16* PROJ, const bf16* Ygate, bf16* OG0, bf16* OG1, bf16* OG2, float* LSE, const float* qnw, const float* knw, int bx, int G) {
;     ...
;         if (t + 2 * G < 3072) AT_LOAD(t + 2 * G, half);
	s_mul_i32 s20, s84, 3
	s_add_i32 s20, s20, s51
	v_cmp_gt_f32_e64 s[0:1], s33, v180
	s_cmpk_gt_i32 s20, 0xbff
	s_cbranch_scc1 .LBB0_319
	s_ashr_i32 s22, s20, 4
	s_mul_hi_i32 s23, s22, 0x55555556
	s_lshr_b32 s26, s23, 31
	s_add_i32 s23, s23, s26
	s_and_b32 s21, s20, 15
	s_mul_i32 s23, s23, 3
	s_mul_hi_i32 s20, s20, 0x2aaaaaab
	s_sub_i32 s23, s22, s23
	s_lshr_b32 s22, s20, 31
	s_ashr_i32 s20, s20, 3
	s_add_i32 s20, s20, s22
	s_ashr_i32 s22, s20, 4
	s_lshl_b32 s26, s23, 1
	s_lshl_b32 s20, s20, 6
	s_lshl_b32 s30, -1, s26
	s_mulk_i32 s23, 0xc00
	s_and_b32 s20, s20, 0x3c0
	s_andn2_b32 s30, s21, s30
	s_lshr_b32 s21, s21, s26
	s_or_b32 s20, s23, s20
	s_ashr_i32 s23, s22, 31
	s_lshl_b32 s51, s21, 7
	s_lshl_b64 s[22:23], s[22:23], 11
	s_ashr_i32 s21, s20, 31
	s_or_b32 s22, s22, s30
	s_lshl_b64 s[30:31], s[20:21], 1
	v_mov_b32_e32 v30, v0
	v_mov_b32_e32 v31, v0
	v_add_u32_e32 v76, s51, v182
	s_add_u32 s38, s34, s30
	v_mov_b32_e32 v28, v0
	v_mov_b32_e32 v29, v0
	v_mov_b64_e32 v[34:35], v[30:31]
	v_mov_b64_e32 v[38:39], v[30:31]
	s_addc_u32 s39, s35, s31
	v_cmp_lt_i32_e32 vcc, -1, v76
	v_lshlrev_b32_e32 v78, 1, v108
	v_mov_b64_e32 v[32:33], v[28:29]
	v_mov_b64_e32 v[36:37], v[28:29]
	s_and_saveexec_b64 s[30:31], vcc
	s_cbranch_execz .LBB0_312
	v_mov_b32_e32 v77, v0
	v_lshlrev_b64 v[2:3], s26, v[76:77]
	v_lshl_add_u64 v[2:3], v[2:3], 0, s[22:23]
	v_mov_b64_e32 v[32:33], s[38:39]
	s_movk_i32 s55, 0x4800
	v_mad_u64_u32 v[32:33], vcc, v2, s55, v[32:33]
	v_mov_b32_e32 v2, v33
	v_mad_u64_u32 v[2:3], vcc, v3, s55, v[2:3]
	v_mov_b32_e32 v33, v2
	v_mov_b32_e32 v79, v0
	v_lshl_add_u64 v[2:3], v[32:33], 0, v[78:79]
	v_add_co_u32_e32 v36, vcc, 0x1000, v2
	s_nop 1
	v_addc_co_u32_e32 v37, vcc, 0, v3, vcc
	global_load_dwordx4 v[32:35], v[2:3], off offset:2048
	s_nop 0
	global_load_dwordx4 v[36:39], v[36:37], off

; __device__ __forceinline__ float silu_f(float x) { return x * __builtin_amdgcn_rcpf(1.f + __expf(-x)); }
; __device__ __forceinline__ float gelu_f(float x) { const float u2 = 1.5957691216057308f * (x + 0.044715f * x * x * x); return x * __builtin_amdgcn_rcpf(1.f + __expf(-u2)); }
; __device__ __forceinline__ v4u pack8(const float (&y)[8]) { return (v4u){pk2(y[0], y[1]), pk2(y[2], y[3]), pk2(y[4], y[5]), pk2(y[6], y[7])}; }
;     __device__ __forceinline__ void operator()(const f32x4 (&acc)[2][2][4][2], const pg8::Unit& u, int wr, int wc, int fr, int fq) const {
;     ...
;                     const int row = lrow0 + ai * 128 + m * 16;
;                     const float rs = rsqrtf(ssq[row] * (1.f / 1024.f) + EPS);
;                     float s1 = 0.f, s2 = 0.f;
; #pragma unroll
;                     for (int bj = 0; bj < 2; ++bj) {
;                         const int c = c0 + bj * 128; const size_t off = (size_t)row * 1024 + c;
;                         const f32x4 v0 = acc[ai][bj][m][0] * rs, v1 = acc[ai][bj][m][1] * rs;
;                         const float v[8] = {v0[0], v0[1], v0[2], v0[3], v1[0], v1[1], v1[2], v1[3]};
;                         float y[8];
;                         if (region == 0) {
; #pragma unroll
;                             for (int j = 0; j < 8; ++j) y[j] = gelu_f(v[j]);
;                             *(v4u*)(o0 + off) = pack8(y);
;                         } else if (region == 1) {
; #pragma unroll
;                             for (int j = 0; j < 8; ++j) { y[j] = gelu_f(v[j]); s1 += y[j]; s2 += y[j] * y[j]; }
;                             *(v4u*)(o1 + off) = pack8(y);
;                         } else {
; #pragma unroll
;                             for (int j = 0; j < 8; ++j) y[j] = silu_f(v[j]);
;                             *(v4u*)(Y + off) = pack8(y);
.LBB0_566:
	s_waitcnt lgkmcnt(1)
	v_or_b32_e32 v114, 16, v166
	v_readlane_b32 s0, v252, 60
	v_ashrrev_i32_e32 v115, 31, v114
	v_readlane_b32 s1, v252, 61
	s_and_b64 vcc, exec, s[48:49]
	s_mov_b64 s[2:3], -1
	s_waitcnt lgkmcnt(0)
	v_lshl_add_u64 v[116:117], v[114:115], 2, s[0:1]
	v_mov_b32_e32 v1, v196
	v_fmamk_f32 v1, v1, 0x3a800000, v139
	s_nop 1
	v_rsq_f32_e32 v1, v1
	s_nop 0
	s_nop 0
	v_mov_b32_e32 v116, v1
	v_pk_mul_f32 v[112:113], v[112:113], v[116:117] op_sel_hi:[1,0]
	v_pk_mul_f32 v[120:121], v[110:111], v[116:117] op_sel_hi:[1,0]
	v_pk_mul_f32 v[108:109], v[108:109], v[116:117] op_sel_hi:[1,0]
	v_pk_mul_f32 v[110:111], v[106:107], v[116:117] op_sel_hi:[1,0]
	s_cbranch_vccnz .LBB0_571
	s_and_b64 vcc, exec, s[46:47]
	s_mov_b64 s[0:1], -1
	s_cbranch_vccnz .LBB0_569
	v_mul_f32_e32 v1, 0xbfb8aa3b, v120
	v_exp_f32_e32 v1, v1
	v_mul_f32_e32 v106, 0xbfb8aa3b, v121
	v_exp_f32_e32 v106, v106
	v_mul_f32_e32 v117, 0xbfb8aa3b, v113
	v_add_f32_e32 v1, 1.0, v1
	v_exp_f32_e32 v117, v117
	v_add_f32_e32 v107, 1.0, v106
	v_rcp_f32_e32 v106, v1
	v_mul_f32_e32 v1, 0xbfb8aa3b, v112
	v_exp_f32_e32 v1, v1
	v_mul_f32_e32 v118, 0xbfb8aa3b, v111
	v_exp_f32_e32 v118, v118
	v_rcp_f32_e32 v107, v107
	v_add_f32_e32 v1, 1.0, v1
	v_rcp_f32_e32 v124, v1
	v_add_f32_e32 v1, 1.0, v117
	v_mul_f32_e32 v117, 0xbfb8aa3b, v110
	v_exp_f32_e32 v117, v117
	v_rcp_f32_e32 v125, v1
	s_mov_b64 s[0:1], 0
	v_add_f32_e32 v1, 1.0, v117
	v_mul_f32_e32 v117, 0xbfb8aa3b, v108
	v_rcp_f32_e32 v126, v1
	v_add_f32_e32 v1, 1.0, v118
	v_exp_f32_e32 v117, v117
	v_mul_f32_e32 v118, 0xbfb8aa3b, v109
	v_exp_f32_e32 v118, v118
	v_rcp_f32_e32 v127, v1
	v_add_f32_e32 v1, 1.0, v117
	v_rcp_f32_e32 v128, v1
	v_add_f32_e32 v1, 1.0, v118
	v_rcp_f32_e32 v129, v1
	v_pk_mul_f32 v[118:119], v[120:121], v[106:107]
	v_pk_mul_f32 v[124:125], v[112:113], v[124:125]
	v_pk_mul_f32 v[126:127], v[110:111], v[126:127]
	v_pk_mul_f32 v[128:129], v[108:109], v[128:129]

; __device__ __forceinline__ float silu_f(float x) { return x * __builtin_amdgcn_rcpf(1.f + __expf(-x)); }
; __device__ __forceinline__ float gelu_f(float x) { const float u2 = 1.5957691216057308f * (x + 0.044715f * x * x * x); return x * __builtin_amdgcn_rcpf(1.f + __expf(-u2)); }
; __device__ __forceinline__ v4u pack8(const float (&y)[8]) { return (v4u){pk2(y[0], y[1]), pk2(y[2], y[3]), pk2(y[4], y[5]), pk2(y[6], y[7])}; }
;     __device__ __forceinline__ void operator()(const f32x4 (&acc)[2][2][4][2], const pg8::Unit& u, int wr, int wc, int fr, int fq) const {
;     ...
;                     const int row = lrow0 + ai * 128 + m * 16;
;                     const float rs = rsqrtf(ssq[row] * (1.f / 1024.f) + EPS);
;                     float s1 = 0.f, s2 = 0.f;
; #pragma unroll
;                     for (int bj = 0; bj < 2; ++bj) {
;                         const int c = c0 + bj * 128; const size_t off = (size_t)row * 1024 + c;
;                         const f32x4 v0 = acc[ai][bj][m][0] * rs, v1 = acc[ai][bj][m][1] * rs;
;                         const float v[8] = {v0[0], v0[1], v0[2], v0[3], v1[0], v1[1], v1[2], v1[3]};
;                         float y[8];
;                         if (region == 0) {
; #pragma unroll
;                             for (int j = 0; j < 8; ++j) y[j] = gelu_f(v[j]);
;                             *(v4u*)(o0 + off) = pack8(y);
;                         } else if (region == 1) {
; #pragma unroll
;                             for (int j = 0; j < 8; ++j) { y[j] = gelu_f(v[j]); s1 += y[j]; s2 += y[j] * y[j]; }
;                             *(v4u*)(o1 + off) = pack8(y);
;                         } else {
; #pragma unroll
;                             for (int j = 0; j < 8; ++j) y[j] = silu_f(v[j]);
;                             *(v4u*)(Y + off) = pack8(y);
.LBB0_585:
	s_waitcnt lgkmcnt(1)
	v_or_b32_e32 v98, 32, v166
	v_readlane_b32 s0, v252, 60
	v_ashrrev_i32_e32 v99, 31, v98
	v_readlane_b32 s1, v252, 61
	s_and_b64 vcc, exec, s[48:49]
	s_mov_b64 s[2:3], -1
	s_waitcnt lgkmcnt(0)
	v_lshl_add_u64 v[100:101], v[98:99], 2, s[0:1]
	v_mov_b32_e32 v1, v197
	v_fmamk_f32 v1, v1, 0x3a800000, v139
	s_nop 1
	v_rsq_f32_e32 v1, v1
	s_nop 0
	s_nop 0
	v_mov_b32_e32 v100, v1
	v_pk_mul_f32 v[96:97], v[96:97], v[100:101] op_sel_hi:[1,0]
	v_pk_mul_f32 v[104:105], v[94:95], v[100:101] op_sel_hi:[1,0]
	v_pk_mul_f32 v[92:93], v[92:93], v[100:101] op_sel_hi:[1,0]
	v_pk_mul_f32 v[94:95], v[90:91], v[100:101] op_sel_hi:[1,0]
	s_cbranch_vccnz .LBB0_590
	s_and_b64 vcc, exec, s[46:47]
	s_mov_b64 s[0:1], -1
	s_cbranch_vccnz .LBB0_588
	v_mul_f32_e32 v1, 0xbfb8aa3b, v104
	v_exp_f32_e32 v1, v1
	v_mul_f32_e32 v90, 0xbfb8aa3b, v105
	v_exp_f32_e32 v90, v90
	v_mul_f32_e32 v101, 0xbfb8aa3b, v97
	v_add_f32_e32 v1, 1.0, v1
	v_exp_f32_e32 v101, v101
	v_add_f32_e32 v91, 1.0, v90
	v_rcp_f32_e32 v90, v1
	v_mul_f32_e32 v1, 0xbfb8aa3b, v96
	v_exp_f32_e32 v1, v1
	v_mul_f32_e32 v102, 0xbfb8aa3b, v95
	v_exp_f32_e32 v102, v102
	v_rcp_f32_e32 v91, v91
	v_add_f32_e32 v1, 1.0, v1
	v_rcp_f32_e32 v106, v1
	v_add_f32_e32 v1, 1.0, v101
	v_mul_f32_e32 v101, 0xbfb8aa3b, v94
	v_exp_f32_e32 v101, v101
	v_rcp_f32_e32 v107, v1
	s_mov_b64 s[0:1], 0
	v_add_f32_e32 v1, 1.0, v101
	v_mul_f32_e32 v101, 0xbfb8aa3b, v92
	v_rcp_f32_e32 v108, v1
	v_add_f32_e32 v1, 1.0, v102
	v_exp_f32_e32 v101, v101
	v_mul_f32_e32 v102, 0xbfb8aa3b, v93
	v_exp_f32_e32 v102, v102
	v_rcp_f32_e32 v109, v1
	v_add_f32_e32 v1, 1.0, v101
	v_rcp_f32_e32 v110, v1
	v_add_f32_e32 v1, 1.0, v102
	v_rcp_f32_e32 v111, v1
	v_pk_mul_f32 v[102:103], v[104:105], v[90:91]
	v_pk_mul_f32 v[106:107], v[96:97], v[106:107]
	v_pk_mul_f32 v[108:109], v[94:95], v[108:109]
	v_pk_mul_f32 v[110:111], v[92:93], v[110:111]

; __device__ __forceinline__ float silu_f(float x) { return x * __builtin_amdgcn_rcpf(1.f + __expf(-x)); }
; __device__ __forceinline__ float gelu_f(float x) { const float u2 = 1.5957691216057308f * (x + 0.044715f * x * x * x); return x * __builtin_amdgcn_rcpf(1.f + __expf(-u2)); }
; __device__ __forceinline__ v4u pack8(const float (&y)[8]) { return (v4u){pk2(y[0], y[1]), pk2(y[2], y[3]), pk2(y[4], y[5]), pk2(y[6], y[7])}; }
;     __device__ __forceinline__ void operator()(const f32x4 (&acc)[2][2][4][2], const pg8::Unit& u, int wr, int wc, int fr, int fq) const {
;     ...
;                     const int row = lrow0 + ai * 128 + m * 16;
;                     const float rs = rsqrtf(ssq[row] * (1.f / 1024.f) + EPS);
;                     float s1 = 0.f, s2 = 0.f;
; #pragma unroll
;                     for (int bj = 0; bj < 2; ++bj) {
;                         const int c = c0 + bj * 128; const size_t off = (size_t)row * 1024 + c;
;                         const f32x4 v0 = acc[ai][bj][m][0] * rs, v1 = acc[ai][bj][m][1] * rs;
;                         const float v[8] = {v0[0], v0[1], v0[2], v0[3], v1[0], v1[1], v1[2], v1[3]};
;                         float y[8];
;                         if (region == 0) {
; #pragma unroll
;                             for (int j = 0; j < 8; ++j) y[j] = gelu_f(v[j]);
;                             *(v4u*)(o0 + off) = pack8(y);
;                         } else if (region == 1) {
; #pragma unroll
;                             for (int j = 0; j < 8; ++j) { y[j] = gelu_f(v[j]); s1 += y[j]; s2 += y[j] * y[j]; }
;                             *(v4u*)(o1 + off) = pack8(y);
;                         } else {
; #pragma unroll
;                             for (int j = 0; j < 8; ++j) y[j] = silu_f(v[j]);
;                             *(v4u*)(Y + off) = pack8(y);
.LBB0_604:
	s_waitcnt lgkmcnt(1)
	v_or_b32_e32 v82, 48, v166
	v_readlane_b32 s0, v252, 60
	v_ashrrev_i32_e32 v83, 31, v82
	v_readlane_b32 s1, v252, 61
	s_and_b64 vcc, exec, s[48:49]
	s_mov_b64 s[2:3], -1
	s_waitcnt lgkmcnt(0)
	v_lshl_add_u64 v[84:85], v[82:83], 2, s[0:1]
	v_mov_b32_e32 v1, v198
	v_fmamk_f32 v1, v1, 0x3a800000, v139
	s_nop 1
	v_rsq_f32_e32 v1, v1
	s_nop 0
	s_nop 0
	v_mov_b32_e32 v84, v1
	v_pk_mul_f32 v[80:81], v[80:81], v[84:85] op_sel_hi:[1,0]
	v_pk_mul_f32 v[88:89], v[78:79], v[84:85] op_sel_hi:[1,0]
	v_pk_mul_f32 v[76:77], v[76:77], v[84:85] op_sel_hi:[1,0]
	v_pk_mul_f32 v[78:79], v[74:75], v[84:85] op_sel_hi:[1,0]
	s_cbranch_vccnz .LBB0_609
	s_and_b64 vcc, exec, s[46:47]
	s_mov_b64 s[0:1], -1
	s_cbranch_vccnz .LBB0_607
	v_mul_f32_e32 v1, 0xbfb8aa3b, v88
	v_exp_f32_e32 v1, v1
	v_mul_f32_e32 v74, 0xbfb8aa3b, v89
	v_exp_f32_e32 v74, v74
	v_mul_f32_e32 v85, 0xbfb8aa3b, v81
	v_add_f32_e32 v1, 1.0, v1
	v_exp_f32_e32 v85, v85
	v_add_f32_e32 v75, 1.0, v74
	v_rcp_f32_e32 v74, v1
	v_mul_f32_e32 v1, 0xbfb8aa3b, v80
	v_exp_f32_e32 v1, v1
	v_mul_f32_e32 v86, 0xbfb8aa3b, v79
	v_exp_f32_e32 v86, v86
	v_rcp_f32_e32 v75, v75
	v_add_f32_e32 v1, 1.0, v1
	v_rcp_f32_e32 v90, v1
	v_add_f32_e32 v1, 1.0, v85
	v_mul_f32_e32 v85, 0xbfb8aa3b, v78
	v_exp_f32_e32 v85, v85
	v_rcp_f32_e32 v91, v1
	s_mov_b64 s[0:1], 0
	v_add_f32_e32 v1, 1.0, v85
	v_mul_f32_e32 v85, 0xbfb8aa3b, v76
	v_rcp_f32_e32 v92, v1
	v_add_f32_e32 v1, 1.0, v86
	v_exp_f32_e32 v85, v85
	v_mul_f32_e32 v86, 0xbfb8aa3b, v77
	v_exp_f32_e32 v86, v86
	v_rcp_f32_e32 v93, v1
	v_add_f32_e32 v1, 1.0, v85
	v_rcp_f32_e32 v94, v1
	v_add_f32_e32 v1, 1.0, v86
	v_rcp_f32_e32 v95, v1
	v_pk_mul_f32 v[86:87], v[88:89], v[74:75]
	v_pk_mul_f32 v[90:91], v[80:81], v[90:91]
	v_pk_mul_f32 v[92:93], v[78:79], v[92:93]
	v_pk_mul_f32 v[94:95], v[76:77], v[94:95]

; __device__ __forceinline__ float silu_f(float x) { return x * __builtin_amdgcn_rcpf(1.f + __expf(-x)); }
; __device__ __forceinline__ float gelu_f(float x) { const float u2 = 1.5957691216057308f * (x + 0.044715f * x * x * x); return x * __builtin_amdgcn_rcpf(1.f + __expf(-u2)); }
; __device__ __forceinline__ v4u pack8(const float (&y)[8]) { return (v4u){pk2(y[0], y[1]), pk2(y[2], y[3]), pk2(y[4], y[5]), pk2(y[6], y[7])}; }
;     __device__ __forceinline__ void operator()(const f32x4 (&acc)[2][2][4][2], const pg8::Unit& u, int wr, int wc, int fr, int fq) const {
;     ...
;                     const int row = lrow0 + ai * 128 + m * 16;
;                     const float rs = rsqrtf(ssq[row] * (1.f / 1024.f) + EPS);
;                     float s1 = 0.f, s2 = 0.f;
; #pragma unroll
;                     for (int bj = 0; bj < 2; ++bj) {
;                         const int c = c0 + bj * 128; const size_t off = (size_t)row * 1024 + c;
;                         const f32x4 v0 = acc[ai][bj][m][0] * rs, v1 = acc[ai][bj][m][1] * rs;
;                         const float v[8] = {v0[0], v0[1], v0[2], v0[3], v1[0], v1[1], v1[2], v1[3]};
;                         float y[8];
;                         if (region == 0) {
; #pragma unroll
;                             for (int j = 0; j < 8; ++j) y[j] = gelu_f(v[j]);
;                             *(v4u*)(o0 + off) = pack8(y);
;                         } else if (region == 1) {
; #pragma unroll
;                             for (int j = 0; j < 8; ++j) { y[j] = gelu_f(v[j]); s1 += y[j]; s2 += y[j] * y[j]; }
;                             *(v4u*)(o1 + off) = pack8(y);
;                         } else {
; #pragma unroll
;                             for (int j = 0; j < 8; ++j) y[j] = silu_f(v[j]);
;                             *(v4u*)(Y + off) = pack8(y);
.LBB0_623:
	v_mov_b32_e32 v1, v199
	s_and_b64 vcc, exec, s[48:49]
	s_mov_b64 s[2:3], -1
	v_fmamk_f32 v1, v1, 0x3a800000, v139
	s_waitcnt lgkmcnt(1)
	s_nop 1
	v_rsq_f32_e32 v1, v1
	s_nop 0
	s_nop 0
	v_mov_b32_e32 v66, v1
	v_pk_mul_f32 v[64:65], v[64:65], v[66:67] op_sel_hi:[1,0]
	v_pk_mul_f32 v[70:71], v[62:63], v[66:67] op_sel_hi:[1,0]
	v_pk_mul_f32 v[62:63], v[60:61], v[66:67] op_sel_hi:[1,0]
	v_pk_mul_f32 v[58:59], v[58:59], v[66:67] op_sel_hi:[1,0]
	s_cbranch_vccnz .LBB0_628
	s_and_b64 vcc, exec, s[46:47]
	s_mov_b64 s[0:1], -1
	s_cbranch_vccnz .LBB0_626
	v_mul_f32_e32 v1, 0xbfb8aa3b, v70
	v_exp_f32_e32 v1, v1
	v_mul_f32_e32 v60, 0xbfb8aa3b, v71
	v_exp_f32_e32 v60, v60
	v_mul_f32_e32 v67, 0xbfb8aa3b, v65
	v_add_f32_e32 v1, 1.0, v1
	v_exp_f32_e32 v67, v67
	v_add_f32_e32 v61, 1.0, v60
	v_rcp_f32_e32 v60, v1
	v_mul_f32_e32 v1, 0xbfb8aa3b, v64
	v_exp_f32_e32 v1, v1
	s_waitcnt lgkmcnt(0)
	v_mul_f32_e32 v68, 0xbfb8aa3b, v59
	v_exp_f32_e32 v68, v68
	v_rcp_f32_e32 v61, v61
	v_add_f32_e32 v1, 1.0, v1
	v_rcp_f32_e32 v72, v1
	v_add_f32_e32 v1, 1.0, v67
	v_mul_f32_e32 v67, 0xbfb8aa3b, v58
	v_exp_f32_e32 v67, v67
	v_rcp_f32_e32 v73, v1
	s_mov_b64 s[0:1], 0
	v_add_f32_e32 v1, 1.0, v67
	v_mul_f32_e32 v67, 0xbfb8aa3b, v62
	v_rcp_f32_e32 v74, v1
	v_add_f32_e32 v1, 1.0, v68
	v_exp_f32_e32 v67, v67
	v_mul_f32_e32 v68, 0xbfb8aa3b, v63
	v_exp_f32_e32 v68, v68
	v_rcp_f32_e32 v75, v1
	v_add_f32_e32 v1, 1.0, v67
	v_rcp_f32_e32 v76, v1
	v_add_f32_e32 v1, 1.0, v68
	v_rcp_f32_e32 v77, v1
	v_pk_mul_f32 v[68:69], v[70:71], v[60:61]
	v_pk_mul_f32 v[72:73], v[64:65], v[72:73]
	v_pk_mul_f32 v[74:75], v[58:59], v[74:75]
	v_pk_mul_f32 v[76:77], v[62:63], v[76:77]

; __device__ __forceinline__ float silu_f(float x) { return x * __builtin_amdgcn_rcpf(1.f + __expf(-x)); }
; __device__ __forceinline__ float gelu_f(float x) { const float u2 = 1.5957691216057308f * (x + 0.044715f * x * x * x); return x * __builtin_amdgcn_rcpf(1.f + __expf(-u2)); }
; __device__ __forceinline__ v4u pack8(const float (&y)[8]) { return (v4u){pk2(y[0], y[1]), pk2(y[2], y[3]), pk2(y[4], y[5]), pk2(y[6], y[7])}; }
;     __device__ __forceinline__ void operator()(const f32x4 (&acc)[2][2][4][2], const pg8::Unit& u, int wr, int wc, int fr, int fq) const {
;     ...
;                     const int row = lrow0 + ai * 128 + m * 16;
;                     const float rs = rsqrtf(ssq[row] * (1.f / 1024.f) + EPS);
;                     float s1 = 0.f, s2 = 0.f;
; #pragma unroll
;                     for (int bj = 0; bj < 2; ++bj) {
;                         const int c = c0 + bj * 128; const size_t off = (size_t)row * 1024 + c;
;                         const f32x4 v0 = acc[ai][bj][m][0] * rs, v1 = acc[ai][bj][m][1] * rs;
;                         const float v[8] = {v0[0], v0[1], v0[2], v0[3], v1[0], v1[1], v1[2], v1[3]};
;                         float y[8];
;                         if (region == 0) {
; #pragma unroll
;                             for (int j = 0; j < 8; ++j) y[j] = gelu_f(v[j]);
;                             *(v4u*)(o0 + off) = pack8(y);
;                         } else if (region == 1) {
; #pragma unroll
;                             for (int j = 0; j < 8; ++j) { y[j] = gelu_f(v[j]); s1 += y[j]; s2 += y[j] * y[j]; }
;                             *(v4u*)(o1 + off) = pack8(y);
;                         } else {
; #pragma unroll
;                             for (int j = 0; j < 8; ++j) y[j] = silu_f(v[j]);
;                             *(v4u*)(Y + off) = pack8(y);
.LBB0_642:
	v_mov_b32_e32 v1, v200
	s_and_b64 vcc, exec, s[48:49]
	s_mov_b64 s[2:3], -1
	v_fmamk_f32 v1, v1, 0x3a800000, v139
	s_waitcnt lgkmcnt(1)
	s_nop 1
	v_rsq_f32_e32 v1, v1
	s_nop 0
	s_nop 0
	v_mov_b32_e32 v50, v1
	v_pk_mul_f32 v[48:49], v[48:49], v[50:51] op_sel_hi:[1,0]
	v_pk_mul_f32 v[54:55], v[46:47], v[50:51] op_sel_hi:[1,0]
	v_pk_mul_f32 v[46:47], v[44:45], v[50:51] op_sel_hi:[1,0]
	v_pk_mul_f32 v[42:43], v[42:43], v[50:51] op_sel_hi:[1,0]
	s_cbranch_vccnz .LBB0_647
	s_and_b64 vcc, exec, s[46:47]
	s_mov_b64 s[0:1], -1
	s_cbranch_vccnz .LBB0_645
	v_mul_f32_e32 v1, 0xbfb8aa3b, v54
	v_exp_f32_e32 v1, v1
	v_mul_f32_e32 v44, 0xbfb8aa3b, v55
	v_exp_f32_e32 v44, v44
	v_mul_f32_e32 v51, 0xbfb8aa3b, v49
	v_add_f32_e32 v1, 1.0, v1
	v_exp_f32_e32 v51, v51
	v_add_f32_e32 v45, 1.0, v44
	v_rcp_f32_e32 v44, v1
	v_mul_f32_e32 v1, 0xbfb8aa3b, v48
	v_exp_f32_e32 v1, v1
	s_waitcnt lgkmcnt(0)
	v_mul_f32_e32 v52, 0xbfb8aa3b, v43
	v_exp_f32_e32 v52, v52
	v_rcp_f32_e32 v45, v45
	v_add_f32_e32 v1, 1.0, v1
	v_rcp_f32_e32 v56, v1
	v_add_f32_e32 v1, 1.0, v51
	v_mul_f32_e32 v51, 0xbfb8aa3b, v42
	v_exp_f32_e32 v51, v51
	v_rcp_f32_e32 v57, v1
	s_mov_b64 s[0:1], 0
	v_add_f32_e32 v1, 1.0, v51
	v_mul_f32_e32 v51, 0xbfb8aa3b, v46
	v_rcp_f32_e32 v58, v1
	v_add_f32_e32 v1, 1.0, v52
	v_exp_f32_e32 v51, v51
	v_mul_f32_e32 v52, 0xbfb8aa3b, v47
	v_exp_f32_e32 v52, v52
	v_rcp_f32_e32 v59, v1
	v_add_f32_e32 v1, 1.0, v51
	v_rcp_f32_e32 v60, v1
	v_add_f32_e32 v1, 1.0, v52
	v_rcp_f32_e32 v61, v1
	v_pk_mul_f32 v[52:53], v[54:55], v[44:45]
	v_pk_mul_f32 v[56:57], v[48:49], v[56:57]
	v_pk_mul_f32 v[58:59], v[42:43], v[58:59]
	v_pk_mul_f32 v[60:61], v[46:47], v[60:61]

; __device__ __forceinline__ float silu_f(float x) { return x * __builtin_amdgcn_rcpf(1.f + __expf(-x)); }
; __device__ __forceinline__ float gelu_f(float x) { const float u2 = 1.5957691216057308f * (x + 0.044715f * x * x * x); return x * __builtin_amdgcn_rcpf(1.f + __expf(-u2)); }
; __device__ __forceinline__ v4u pack8(const float (&y)[8]) { return (v4u){pk2(y[0], y[1]), pk2(y[2], y[3]), pk2(y[4], y[5]), pk2(y[6], y[7])}; }
;     __device__ __forceinline__ void operator()(const f32x4 (&acc)[2][2][4][2], const pg8::Unit& u, int wr, int wc, int fr, int fq) const {
;     ...
;                     const int row = lrow0 + ai * 128 + m * 16;
;                     const float rs = rsqrtf(ssq[row] * (1.f / 1024.f) + EPS);
;                     float s1 = 0.f, s2 = 0.f;
; #pragma unroll
;                     for (int bj = 0; bj < 2; ++bj) {
;                         const int c = c0 + bj * 128; const size_t off = (size_t)row * 1024 + c;
;                         const f32x4 v0 = acc[ai][bj][m][0] * rs, v1 = acc[ai][bj][m][1] * rs;
;                         const float v[8] = {v0[0], v0[1], v0[2], v0[3], v1[0], v1[1], v1[2], v1[3]};
;                         float y[8];
;                         if (region == 0) {
; #pragma unroll
;                             for (int j = 0; j < 8; ++j) y[j] = gelu_f(v[j]);
;                             *(v4u*)(o0 + off) = pack8(y);
;                         } else if (region == 1) {
; #pragma unroll
;                             for (int j = 0; j < 8; ++j) { y[j] = gelu_f(v[j]); s1 += y[j]; s2 += y[j] * y[j]; }
;                             *(v4u*)(o1 + off) = pack8(y);
;                         } else {
; #pragma unroll
;                             for (int j = 0; j < 8; ++j) y[j] = silu_f(v[j]);
;                             *(v4u*)(Y + off) = pack8(y);
.LBB0_661:
	v_mov_b32_e32 v1, v201
	s_and_b64 vcc, exec, s[48:49]
	s_mov_b64 s[2:3], -1
	v_fmamk_f32 v1, v1, 0x3a800000, v139
	s_waitcnt lgkmcnt(1)
	s_nop 1
	v_rsq_f32_e32 v1, v1
	s_nop 0
	s_nop 0
	v_mov_b32_e32 v34, v1
	v_pk_mul_f32 v[32:33], v[32:33], v[34:35] op_sel_hi:[1,0]
	v_pk_mul_f32 v[38:39], v[30:31], v[34:35] op_sel_hi:[1,0]
	v_pk_mul_f32 v[30:31], v[28:29], v[34:35] op_sel_hi:[1,0]
	v_pk_mul_f32 v[26:27], v[26:27], v[34:35] op_sel_hi:[1,0]
	s_cbranch_vccnz .LBB0_666
	s_and_b64 vcc, exec, s[46:47]
	s_mov_b64 s[0:1], -1
	s_cbranch_vccnz .LBB0_664
	v_mul_f32_e32 v1, 0xbfb8aa3b, v38
	v_exp_f32_e32 v1, v1
	v_mul_f32_e32 v28, 0xbfb8aa3b, v39
	v_exp_f32_e32 v28, v28
	v_mul_f32_e32 v35, 0xbfb8aa3b, v33
	v_add_f32_e32 v1, 1.0, v1
	v_exp_f32_e32 v35, v35
	v_add_f32_e32 v29, 1.0, v28
	v_rcp_f32_e32 v28, v1
	v_mul_f32_e32 v1, 0xbfb8aa3b, v32
	v_exp_f32_e32 v1, v1
	s_waitcnt lgkmcnt(0)
	v_mul_f32_e32 v36, 0xbfb8aa3b, v27
	v_exp_f32_e32 v36, v36
	v_rcp_f32_e32 v29, v29
	v_add_f32_e32 v1, 1.0, v1
	v_rcp_f32_e32 v40, v1
	v_add_f32_e32 v1, 1.0, v35
	v_mul_f32_e32 v35, 0xbfb8aa3b, v26
	v_exp_f32_e32 v35, v35
	v_rcp_f32_e32 v41, v1
	s_mov_b64 s[0:1], 0
	v_add_f32_e32 v1, 1.0, v35
	v_mul_f32_e32 v35, 0xbfb8aa3b, v30
	v_rcp_f32_e32 v42, v1
	v_add_f32_e32 v1, 1.0, v36
	v_exp_f32_e32 v35, v35
	v_mul_f32_e32 v36, 0xbfb8aa3b, v31
	v_exp_f32_e32 v36, v36
	v_rcp_f32_e32 v43, v1
	v_add_f32_e32 v1, 1.0, v35
	v_rcp_f32_e32 v44, v1
	v_add_f32_e32 v1, 1.0, v36
	v_rcp_f32_e32 v45, v1
	v_pk_mul_f32 v[36:37], v[38:39], v[28:29]
	v_pk_mul_f32 v[40:41], v[32:33], v[40:41]
	v_pk_mul_f32 v[42:43], v[26:27], v[42:43]
	v_pk_mul_f32 v[44:45], v[30:31], v[44:45]

; __device__ __forceinline__ float silu_f(float x) { return x * __builtin_amdgcn_rcpf(1.f + __expf(-x)); }
; __device__ __forceinline__ float gelu_f(float x) { const float u2 = 1.5957691216057308f * (x + 0.044715f * x * x * x); return x * __builtin_amdgcn_rcpf(1.f + __expf(-u2)); }
; __device__ __forceinline__ v4u pack8(const float (&y)[8]) { return (v4u){pk2(y[0], y[1]), pk2(y[2], y[3]), pk2(y[4], y[5]), pk2(y[6], y[7])}; }
;     __device__ __forceinline__ void operator()(const f32x4 (&acc)[2][2][4][2], const pg8::Unit& u, int wr, int wc, int fr, int fq) const {
;     ...
;                     const int row = lrow0 + ai * 128 + m * 16;
;                     const float rs = rsqrtf(ssq[row] * (1.f / 1024.f) + EPS);
;                     float s1 = 0.f, s2 = 0.f;
; #pragma unroll
;                     for (int bj = 0; bj < 2; ++bj) {
;                         const int c = c0 + bj * 128; const size_t off = (size_t)row * 1024 + c;
;                         const f32x4 v0 = acc[ai][bj][m][0] * rs, v1 = acc[ai][bj][m][1] * rs;
;                         const float v[8] = {v0[0], v0[1], v0[2], v0[3], v1[0], v1[1], v1[2], v1[3]};
;                         float y[8];
;                         if (region == 0) {
; #pragma unroll
;                             for (int j = 0; j < 8; ++j) y[j] = gelu_f(v[j]);
;                             *(v4u*)(o0 + off) = pack8(y);
;                         } else if (region == 1) {
; #pragma unroll
;                             for (int j = 0; j < 8; ++j) { y[j] = gelu_f(v[j]); s1 += y[j]; s2 += y[j] * y[j]; }
;                             *(v4u*)(o1 + off) = pack8(y);
;                         } else {
; #pragma unroll
;                             for (int j = 0; j < 8; ++j) y[j] = silu_f(v[j]);
;                             *(v4u*)(Y + off) = pack8(y);
.LBB0_680:
	v_mov_b32_e32 v1, v202
	s_and_b64 vcc, exec, s[48:49]
	s_mov_b64 s[2:3], -1
	v_fmamk_f32 v1, v1, 0x3a800000, v139
	s_waitcnt lgkmcnt(1)
	s_nop 1
	v_rsq_f32_e32 v1, v1
	s_nop 0
	s_nop 0
	v_mov_b32_e32 v18, v1
	v_pk_mul_f32 v[16:17], v[16:17], v[18:19] op_sel_hi:[1,0]
	v_pk_mul_f32 v[22:23], v[14:15], v[18:19] op_sel_hi:[1,0]
	v_pk_mul_f32 v[14:15], v[12:13], v[18:19] op_sel_hi:[1,0]
	v_pk_mul_f32 v[10:11], v[10:11], v[18:19] op_sel_hi:[1,0]
	s_cbranch_vccnz .LBB0_685
	s_and_b64 vcc, exec, s[46:47]
	s_mov_b64 s[0:1], -1
	s_cbranch_vccnz .LBB0_683
	v_mul_f32_e32 v1, 0xbfb8aa3b, v22
	v_exp_f32_e32 v1, v1
	v_mul_f32_e32 v12, 0xbfb8aa3b, v23
	v_exp_f32_e32 v12, v12
	v_mul_f32_e32 v19, 0xbfb8aa3b, v17
	v_add_f32_e32 v1, 1.0, v1
	v_exp_f32_e32 v19, v19
	v_add_f32_e32 v13, 1.0, v12
	v_rcp_f32_e32 v12, v1
	v_mul_f32_e32 v1, 0xbfb8aa3b, v16
	v_exp_f32_e32 v1, v1
	s_waitcnt lgkmcnt(0)
	v_mul_f32_e32 v20, 0xbfb8aa3b, v11
	v_exp_f32_e32 v20, v20
	v_rcp_f32_e32 v13, v13
	v_add_f32_e32 v1, 1.0, v1
	v_rcp_f32_e32 v24, v1
	v_add_f32_e32 v1, 1.0, v19
	v_mul_f32_e32 v19, 0xbfb8aa3b, v10
	v_exp_f32_e32 v19, v19
	v_rcp_f32_e32 v25, v1
	s_mov_b64 s[0:1], 0
	v_add_f32_e32 v1, 1.0, v19
	v_mul_f32_e32 v19, 0xbfb8aa3b, v14
	v_rcp_f32_e32 v26, v1
	v_add_f32_e32 v1, 1.0, v20
	v_exp_f32_e32 v19, v19
	v_mul_f32_e32 v20, 0xbfb8aa3b, v15
	v_exp_f32_e32 v20, v20
	v_rcp_f32_e32 v27, v1
	v_add_f32_e32 v1, 1.0, v19
	v_rcp_f32_e32 v28, v1
	v_add_f32_e32 v1, 1.0, v20
	v_rcp_f32_e32 v29, v1
	v_pk_mul_f32 v[20:21], v[22:23], v[12:13]
	v_pk_mul_f32 v[24:25], v[16:17], v[24:25]
	v_pk_mul_f32 v[26:27], v[10:11], v[26:27]
	v_pk_mul_f32 v[28:29], v[14:15], v[28:29]

; #define LAS __attribute__((address_space(3)))
; __device__ __forceinline__ float bflo(unsigned u) { return __uint_as_float(u << 16); }
; __device__ __forceinline__ float bfhi(unsigned u) { return __uint_as_float(u & 0xffff0000u); }
; __device__ __forceinline__ unsigned short f2bf(float f) { return (unsigned short)(pk2(f, 0.f) & 0xffffu); }
; __device__ __forceinline__ void gmlp_unit(LAS unsigned char* lds, int unit, const bf16* U, const bf16* Vb, bf16* Y, const float* vs1, const float* vs2,
;                                           const float* lnw, const float* lnb, const float* bs) {
;     ...
;     const int t = 16 * w + l16;
;     v4u uu[4], gg[4];
; #pragma unroll
;     for (int j = 0; j < 4; ++j) { const size_t off = (m0 + t) * 1024 + c0 + 32 * j + 8 * g4; uu[j] = *(const v4u*)(U + off); gg[j] = *(const v4u*)(Y + off); }
;     {
;         const int s = tid >> 2, cq = (tid & 3) * 32;
;         const size_t row = m0 + s;
;         const float mean = vs1[row] * (1.f / 1024.f); const float var = vs2[row] * (1.f / 1024.f) - mean * mean; const float rstd = rsqrtf(fmaxf(var, 0.f) + EPS);
; #pragma unroll
;         for (int j = 0; j < 4; ++j) {
;             const int cc = cq + 8 * j;
;             const v4u vr = *(const v4u*)(Vb + row * 1024 + c0 + cc);
;             const f32x4 w0 = *(const f32x4*)(lnw + c0 + cc), w1 = *(const f32x4*)(lnw + c0 + cc + 4), b0 = *(const f32x4*)(lnb + c0 + cc), b1 = *(const f32x4*)(lnb + c0 + cc + 4);
;             LAS bf16* vd = Vt + cc * 136 + s;
;             vd[0 * 136] = f2bf((bflo(vr.x) - mean) * rstd * w0[0] + b0[0]); vd[1 * 136] = f2bf((bfhi(vr.x) - mean) * rstd * w0[1] + b0[1]);
;             vd[2 * 136] = f2bf((bflo(vr.y) - mean) * rstd * w0[2] + b0[2]); vd[3 * 136] = f2bf((bfhi(vr.y) - mean) * rstd * w0[3] + b0[3]);
;             vd[4 * 136] = f2bf((bflo(vr.z) - mean) * rstd * w1[0] + b1[0]); vd[5 * 136] = f2bf((bfhi(vr.z) - mean) * rstd * w1[1] + b1[1]);
;             vd[6 * 136] = f2bf((bflo(vr.w) - mean) * rstd * w1[2] + b1[2]); vd[7 * 136] = f2bf((bfhi(vr.w) - mean) * rstd * w1[3] + b1[3]);
;         }
;     }
;     LBAR();
;     bf16x8 bw[4];
; #pragma unroll
;     for (int ks = 0; ks < 4; ++ks) bw[ks] = *(const LAS bf16x8*)(Wa + (16 * w + l16) * 136 + 32 * ks + 8 * g4);
;     const float bias = bs[g * 128 + t];
.LBB0_765:
	v_mov_b32_e32 v1, v145
	s_ashr_i32 s0, s7, 3
	v_readfirstlane_b32 s2, v1
	s_ashr_i32 s2, s2, 2
	s_ashr_i32 s1, s0, 31
	v_bfi_b32 v84, -16, s2, v1
	s_lshl_b64 s[0:1], s[0:1], 7
	v_ashrrev_i32_e32 v85, 31, v84
	v_lshl_add_u64 v[82:83], s[0:1], 0, v[84:85]
	v_lshlrev_b64 v[2:3], 10, v[82:83]
	v_ashrrev_i32_e32 v34, 2, v1
	v_lshlrev_b32_e32 v35, 5, v1
	v_bfe_u32 v88, v1, 4, 2
	v_or_b32_e32 v2, s26, v2
	v_and_b32_e32 v90, 0x60, v35
	v_ashrrev_i32_e32 v35, 31, v34
	v_or_b32_e32 v3, s27, v3
	v_lshl_or_b32 v2, v88, 3, v2
	v_lshl_add_u64 v[36:37], s[0:1], 0, v[34:35]
	v_readlane_b32 s0, v251, 21
	v_lshlrev_b64 v[2:3], 1, v[2:3]
	v_lshlrev_b64 v[38:39], 2, v[36:37]
	v_readlane_b32 s1, v251, 22
	v_lshl_add_u64 v[4:5], s[34:35], 0, v[2:3]
	global_load_dwordx4 v[30:33], v[4:5], off
	v_lshl_add_u64 v[40:41], s[0:1], 0, v[38:39]
	global_load_dword v197, v[40:41], off
	v_lshl_add_u64 v[4:5], s[50:51], 0, v[2:3]
	global_load_dwordx4 v[26:29], v[4:5], off
	v_or_b32_e32 v4, 64, v2
	v_mov_b32_e32 v5, v3
	v_lshl_add_u64 v[6:7], s[34:35], 0, v[4:5]
	v_lshl_add_u64 v[4:5], s[50:51], 0, v[4:5]
	global_load_dwordx4 v[22:25], v[6:7], off
	global_load_dwordx4 v[18:21], v[4:5], off
	v_or_b32_e32 v4, 0x80, v2
	v_mov_b32_e32 v5, v3
	v_readlane_b32 s0, v251, 23
	v_lshl_add_u64 v[6:7], s[34:35], 0, v[4:5]
	v_lshl_add_u64 v[4:5], s[50:51], 0, v[4:5]
	v_or_b32_e32 v2, 0xc0, v2
	v_readlane_b32 s1, v251, 24
	global_load_dwordx4 v[14:17], v[6:7], off
	global_load_dwordx4 v[10:13], v[4:5], off
	v_lshl_add_u64 v[4:5], s[34:35], 0, v[2:3]
	v_lshl_add_u64 v[2:3], s[50:51], 0, v[2:3]
	v_lshl_add_u64 v[38:39], s[0:1], 0, v[38:39]
	global_load_dwordx4 v[6:9], v[4:5], off
	global_load_dword v196, v[38:39], off
	global_load_dwordx4 v[2:5], v[2:3], off
	v_lshlrev_b64 v[36:37], 11, v[36:37]
	v_readlane_b32 s36, v251, 5
	s_lshl_b64 s[2:3], s[26:27], 2
	v_readlane_b32 s42, v251, 11
	v_readlane_b32 s43, v251, 12
	v_readlane_b32 s44, v251, 13
	v_readlane_b32 s45, v251, 14
	v_lshlrev_b32_e32 v89, 2, v90
	v_readlane_b32 s48, v251, 17
	v_readlane_b32 s49, v251, 18
	v_readlane_b32 s50, v251, 19
	v_readlane_b32 s51, v251, 20
	v_readlane_b32 s50, v255, 24
	v_readlane_b32 s51, v255, 25
	v_readlane_b32 s37, v251, 6
	v_readlane_b32 s38, v251, 7
	v_readlane_b32 s39, v251, 8
	v_readlane_b32 s40, v251, 9
	v_readlane_b32 s41, v251, 10
	v_readlane_b32 s46, v251, 15
	v_readlane_b32 s47, v251, 16
	v_readlane_b32 s0, v253, 0
	v_readlane_b32 s1, v253, 1
	v_lshlrev_b32_e32 v235, 1, v34
	v_lshlrev_b32_e32 v34, 1, v90
	v_lshl_add_u64 v[36:37], s[0:1], 0, v[36:37]
	s_lshl_b64 s[0:1], s[26:27], 1
	v_lshl_add_u64 v[36:37], v[36:37], 0, s[0:1]
	v_mov_b32_e32 v35, v0
	v_lshl_add_u64 v[46:47], v[36:37], 0, v[34:35]
	s_add_u32 s4, s42, s2
	global_load_dwordx4 v[34:37], v[46:47], off offset:48
	global_load_dwordx4 v[38:41], v[46:47], off offset:32
	global_load_dwordx4 v[42:45], v[46:47], off offset:16
	global_load_dwordx4 v[54:57], v[46:47], off
	s_addc_u32 s5, s43, s3
	s_add_u32 s2, s44, s2
	s_addc_u32 s3, s45, s3
	global_load_dwordx4 v[46:49], v89, s[4:5] offset:48
	global_load_dwordx4 v[58:61], v89, s[4:5] offset:32
	global_load_dwordx4 v[66:69], v89, s[4:5] offset:16
	global_load_dwordx4 v[74:77], v89, s[4:5]
	global_load_dwordx4 v[50:53], v89, s[2:3] offset:48
	global_load_dwordx4 v[62:65], v89, s[2:3] offset:32
	global_load_dwordx4 v[70:73], v89, s[2:3] offset:16
	global_load_dwordx4 v[78:81], v89, s[2:3]
	global_load_dwordx4 v[200:203], v89, s[4:5] offset:112
	global_load_dwordx4 v[204:207], v89, s[4:5] offset:96
	global_load_dwordx4 v[208:211], v89, s[4:5] offset:80
	global_load_dwordx4 v[224:227], v89, s[4:5] offset:64
	global_load_dwordx4 v[212:215], v89, s[2:3] offset:112
	global_load_dwordx4 v[216:219], v89, s[2:3] offset:96
	global_load_dwordx4 v[220:223], v89, s[2:3] offset:80
	global_load_dwordx4 v[228:231], v89, s[2:3] offset:64
	v_add_u32_e32 v198, s26, v84
	v_ashrrev_i32_e32 v199, 31, v198
	v_lshl_add_u64 v[198:199], v[198:199], 2, s[48:49]
	global_load_dword v232, v[198:199], off
	v_mul_u32_u24_e32 v90, 0x110, v90
	s_add_i32 s7, s7, s84
	s_waitcnt vmcnt(0)
	v_mul_f32_e32 v86, 0x3a800000, v196
	v_mul_f32_e32 v87, 0x3a800000, v197
	v_fma_f32 v233, -v87, v87, v86
	v_max_f32_e32 v233, 0, v233
	v_add_f32_e32 v233, 0x358637bd, v233
	v_rsq_f32_e32 v85, v233
	s_nop 0
	v_add3_u32 v86, 0, v235, v90
	v_lshlrev_b32_e32 v90, 16, v54
	v_and_b32_e32 v54, 0xffff0000, v54
	v_sub_f32_e32 v54, v54, v87
	v_mul_f32_e32 v54, v54, v85
	v_fma_f32 v54, v75, v54, v79
	v_cvt_pk_bf16_f32 v54, v54, s0
	ds_write_b16 v86, v54 offset:35088
	v_lshlrev_b32_e32 v54, 16, v55
	v_sub_f32_e32 v54, v54, v87
	v_mul_f32_e32 v54, v54, v85
	v_fma_f32 v54, v76, v54, v80
	v_cvt_pk_bf16_f32 v54, v54, s0
	ds_write_b16 v86, v54 offset:35360
	v_and_b32_e32 v54, 0xffff0000, v55
	v_sub_f32_e32 v54, v54, v87
	v_mul_f32_e32 v54, v54, v85
	v_fmac_f32_e32 v81, v77, v54
	v_cvt_pk_bf16_f32 v54, v81, s0
	ds_write_b16 v86, v54 offset:35632
	v_lshlrev_b32_e32 v54, 16, v56
	v_sub_f32_e32 v54, v54, v87
	v_mul_f32_e32 v54, v54, v85
	v_fma_f32 v54, v66, v54, v70
	v_cvt_pk_bf16_f32 v54, v54, s0
	ds_write_b16 v86, v54 offset:35904
	v_and_b32_e32 v54, 0xffff0000, v56
	v_sub_f32_e32 v54, v54, v87
	v_mul_f32_e32 v54, v54, v85
	v_fma_f32 v54, v67, v54, v71
	v_cvt_pk_bf16_f32 v54, v54, s0
	ds_write_b16 v86, v54 offset:36176
	v_lshlrev_b32_e32 v54, 16, v57
	v_sub_f32_e32 v54, v54, v87
	v_mul_f32_e32 v54, v54, v85
	v_fma_f32 v54, v68, v54, v72
	v_cvt_pk_bf16_f32 v54, v54, s0
	ds_write_b16 v86, v54 offset:36448
	v_and_b32_e32 v54, 0xffff0000, v57
	v_sub_f32_e32 v54, v54, v87
	v_mul_f32_e32 v54, v54, v85
	v_fmac_f32_e32 v73, v69, v54
	v_cvt_pk_bf16_f32 v54, v73, s0
; #define LAS __attribute__((address_space(3)))
; __device__ __forceinline__ float bflo(unsigned u) { return __uint_as_float(u << 16); }
; __device__ __forceinline__ float bfhi(unsigned u) { return __uint_as_float(u & 0xffff0000u); }
; __device__ __forceinline__ unsigned short f2bf(float f) { return (unsigned short)(pk2(f, 0.f) & 0xffffu); }
; #define LBAR() do { asm volatile("s_waitcnt lgkmcnt(0)" ::: "memory"); __builtin_amdgcn_s_barrier(); asm volatile("" ::: "memory"); } while (0)
; __device__ __forceinline__ void gmlp_unit(LAS unsigned char* lds, int unit, const bf16* U, const bf16* Vb, bf16* Y, const float* vs1, const float* vs2,
;                                           const float* lnw, const float* lnb, const float* bs) {
;     ...
; #pragma unroll
;         for (int j = 0; j < 4; ++j) {
;             const int cc = cq + 8 * j;
;             const v4u vr = *(const v4u*)(Vb + row * 1024 + c0 + cc);
;             const f32x4 w0 = *(const f32x4*)(lnw + c0 + cc), w1 = *(const f32x4*)(lnw + c0 + cc + 4), b0 = *(const f32x4*)(lnb + c0 + cc), b1 = *(const f32x4*)(lnb + c0 + cc + 4);
;             LAS bf16* vd = Vt + cc * 136 + s;
;             vd[0 * 136] = f2bf((bflo(vr.x) - mean) * rstd * w0[0] + b0[0]); vd[1 * 136] = f2bf((bfhi(vr.x) - mean) * rstd * w0[1] + b0[1]);
;             vd[2 * 136] = f2bf((bflo(vr.y) - mean) * rstd * w0[2] + b0[2]); vd[3 * 136] = f2bf((bfhi(vr.y) - mean) * rstd * w0[3] + b0[3]);
;             vd[4 * 136] = f2bf((bflo(vr.z) - mean) * rstd * w1[0] + b1[0]); vd[5 * 136] = f2bf((bfhi(vr.z) - mean) * rstd * w1[1] + b1[1]);
;             vd[6 * 136] = f2bf((bflo(vr.w) - mean) * rstd * w1[2] + b1[2]); vd[7 * 136] = f2bf((bfhi(vr.w) - mean) * rstd * w1[3] + b1[3]);
;         }
;     }
;     LBAR();
	ds_write_b16 v86, v54 offset:36720
	v_lshlrev_b32_e32 v54, 16, v42
	v_and_b32_e32 v42, 0xffff0000, v42
	v_sub_f32_e32 v42, v42, v87
	v_mul_f32_e32 v42, v85, v42
	v_fma_f32 v42, v59, v42, v63
	v_cvt_pk_bf16_f32 v42, v42, s0
	ds_write_b16 v86, v42 offset:37264
	v_lshlrev_b32_e32 v42, 16, v43
	v_sub_f32_e32 v42, v42, v87
	v_mul_f32_e32 v42, v85, v42
	v_fma_f32 v42, v60, v42, v64
	v_cvt_pk_bf16_f32 v42, v42, s0
	ds_write_b16 v86, v42 offset:37536
	v_and_b32_e32 v42, 0xffff0000, v43
	v_sub_f32_e32 v42, v42, v87
	v_mul_f32_e32 v42, v85, v42
	v_fmac_f32_e32 v65, v61, v42
	v_cvt_pk_bf16_f32 v42, v65, s0
	ds_write_b16 v86, v42 offset:37808
	v_lshlrev_b32_e32 v42, 16, v44
	v_sub_f32_e32 v42, v42, v87
	v_mul_f32_e32 v42, v85, v42
	v_fma_f32 v42, v46, v42, v50
	v_cvt_pk_bf16_f32 v42, v42, s0
	ds_write_b16 v86, v42 offset:38080
	v_and_b32_e32 v42, 0xffff0000, v44
	v_sub_f32_e32 v42, v42, v87
	v_mul_f32_e32 v42, v85, v42
	v_fma_f32 v42, v47, v42, v51
	v_cvt_pk_bf16_f32 v42, v42, s0
	ds_write_b16 v86, v42 offset:38352
	v_lshlrev_b32_e32 v42, 16, v45
	v_sub_f32_e32 v42, v42, v87
	v_mul_f32_e32 v42, v85, v42
	v_fma_f32 v42, v48, v42, v52
	v_cvt_pk_bf16_f32 v42, v42, s0
	ds_write_b16 v86, v42 offset:38624
	v_and_b32_e32 v42, 0xffff0000, v45
	v_sub_f32_e32 v90, v90, v87
	v_sub_f32_e32 v54, v54, v87
	v_sub_f32_e32 v42, v42, v87
	v_mul_f32_e32 v90, v90, v85
	v_mul_f32_e32 v54, v85, v54
	v_mul_f32_e32 v42, v85, v42
	v_fma_f32 v74, v74, v90, v78
	v_fma_f32 v54, v58, v54, v62
	v_fmac_f32_e32 v53, v49, v42
	v_cvt_pk_bf16_f32 v74, v74, s0
	v_cvt_pk_bf16_f32 v54, v54, s0
	v_cvt_pk_bf16_f32 v42, v53, s0
	ds_write_b16 v86, v74 offset:34816
	ds_write_b16 v86, v54 offset:36992
	ds_write_b16 v86, v42 offset:38896
	v_lshlrev_b32_e32 v74, 16, v38
	v_and_b32_e32 v38, 0xffff0000, v38
	v_sub_f32_e32 v38, v38, v87
	v_mul_f32_e32 v38, v85, v38
	v_sub_f32_e32 v74, v74, v87
	v_mul_f32_e32 v74, v85, v74
	s_movk_i32 s2, 0x110
	v_fma_f32 v38, v225, v38, v229
	v_cvt_pk_bf16_f32 v38, v38, s0
	ds_write_b16 v86, v38 offset:39440
	v_lshlrev_b32_e32 v38, 16, v39
	v_sub_f32_e32 v38, v38, v87
	v_mul_f32_e32 v38, v85, v38
	v_fma_f32 v38, v226, v38, v230
	v_cvt_pk_bf16_f32 v38, v38, s0
	ds_write_b16 v86, v38 offset:39712
	v_and_b32_e32 v38, 0xffff0000, v39
	v_sub_f32_e32 v38, v38, v87
	v_mul_f32_e32 v38, v85, v38
	v_fmac_f32_e32 v231, v227, v38
	v_cvt_pk_bf16_f32 v38, v231, s0
	ds_write_b16 v86, v38 offset:39984
	v_lshlrev_b32_e32 v38, 16, v40
	v_sub_f32_e32 v38, v38, v87
	v_mul_f32_e32 v38, v85, v38
	v_fma_f32 v38, v208, v38, v220
	v_cvt_pk_bf16_f32 v38, v38, s0
	ds_write_b16 v86, v38 offset:40256
	v_and_b32_e32 v38, 0xffff0000, v40
	v_sub_f32_e32 v38, v38, v87
	v_mul_f32_e32 v38, v85, v38
	v_fma_f32 v38, v209, v38, v221
	v_cvt_pk_bf16_f32 v38, v38, s0
	ds_write_b16 v86, v38 offset:40528
	v_lshlrev_b32_e32 v38, 16, v41
	v_sub_f32_e32 v38, v38, v87
	v_mul_f32_e32 v38, v85, v38
	v_fma_f32 v38, v210, v38, v222
	v_cvt_pk_bf16_f32 v38, v38, s0
	ds_write_b16 v86, v38 offset:40800
	v_and_b32_e32 v38, 0xffff0000, v41
	v_sub_f32_e32 v38, v38, v87
	v_mul_f32_e32 v38, v85, v38
	v_fmac_f32_e32 v223, v211, v38
	v_cvt_pk_bf16_f32 v38, v223, s0
	ds_write_b16 v86, v38 offset:41072
	v_lshlrev_b32_e32 v38, 16, v34
	v_and_b32_e32 v34, 0xffff0000, v34
	v_sub_f32_e32 v34, v34, v87
	v_mul_f32_e32 v34, v85, v34
	v_fma_f32 v34, v205, v34, v217
	v_cvt_pk_bf16_f32 v34, v34, s0
	ds_write_b16 v86, v34 offset:41616
	v_lshlrev_b32_e32 v34, 16, v35
	v_sub_f32_e32 v34, v34, v87
	v_mul_f32_e32 v34, v85, v34
	v_fma_f32 v34, v206, v34, v218
	v_cvt_pk_bf16_f32 v34, v34, s0
	ds_write_b16 v86, v34 offset:41888
	v_and_b32_e32 v34, 0xffff0000, v35
	v_sub_f32_e32 v34, v34, v87
	v_mul_f32_e32 v34, v85, v34
	v_fmac_f32_e32 v219, v207, v34
	v_cvt_pk_bf16_f32 v34, v219, s0
	ds_write_b16 v86, v34 offset:42160
	v_lshlrev_b32_e32 v34, 16, v36
	v_sub_f32_e32 v34, v34, v87
	v_mul_f32_e32 v34, v85, v34
	v_fma_f32 v34, v200, v34, v212
	v_cvt_pk_bf16_f32 v34, v34, s0
	ds_write_b16 v86, v34 offset:42432
	v_and_b32_e32 v34, 0xffff0000, v36
	v_sub_f32_e32 v34, v34, v87
	v_mul_f32_e32 v34, v85, v34
	v_fma_f32 v34, v201, v34, v213
	v_cvt_pk_bf16_f32 v34, v34, s0
	ds_write_b16 v86, v34 offset:42704
	v_lshlrev_b32_e32 v34, 16, v37
	v_sub_f32_e32 v34, v34, v87
	v_mul_f32_e32 v34, v85, v34
	v_fma_f32 v34, v202, v34, v214
	v_cvt_pk_bf16_f32 v34, v34, s0
	ds_write_b16 v86, v34 offset:42976
	v_and_b32_e32 v34, 0xffff0000, v37
	v_sub_f32_e32 v38, v38, v87
	v_sub_f32_e32 v34, v34, v87
	v_mul_f32_e32 v38, v85, v38
	v_mul_f32_e32 v34, v85, v34
	v_fma_f32 v224, v224, v74, v228
	v_fma_f32 v38, v204, v38, v216
	v_fmac_f32_e32 v215, v203, v34
	v_cvt_pk_bf16_f32 v224, v224, s0
	v_cvt_pk_bf16_f32 v38, v38, s0
	v_cvt_pk_bf16_f32 v34, v215, s0
	v_add_u32_e32 v50, s26, v84
	ds_write_b16 v86, v224 offset:39168
	ds_write_b16 v86, v38 offset:41344
	ds_write_b16 v86, v34 offset:43248
	v_mul_lo_u32 v34, v84, s2
	v_lshlrev_b32_e32 v54, 4, v88
	v_ashrrev_i32_e32 v51, 31, v50
	s_waitcnt lgkmcnt(0)
	s_barrier
; #define LAS __attribute__((address_space(3)))
; __device__ __forceinline__ float bflo(unsigned u) { return __uint_as_float(u << 16); }
; __device__ __forceinline__ float bfhi(unsigned u) { return __uint_as_float(u & 0xffff0000u); }
; __device__ __forceinline__ unsigned pk2(float lo, float hi) { f32x2_t v = {lo, hi}; bf16x2_t b = __builtin_convertvector(v, bf16x2_t); return __builtin_bit_cast(unsigned, b); }
; __device__ __forceinline__ f32x4 mfma16(bf16x8 a, bf16x8 b, f32x4 c) { return __builtin_amdgcn_mfma_f32_16x16x32_bf16(a, b, c, 0, 0, 0); }
; __device__ __forceinline__ void gmlp_unit(LAS unsigned char* lds, int unit, const bf16* U, const bf16* Vb, bf16* Y, const float* vs1, const float* vs2,
;                                           const float* lnw, const float* lnb, const float* bs) {
;     ...
;     bf16x8 bw[4];
; #pragma unroll
;     for (int ks = 0; ks < 4; ++ks) bw[ks] = *(const LAS bf16x8*)(Wa + (16 * w + l16) * 136 + 32 * ks + 8 * g4);
;     const float bias = bs[g * 128 + t];
; #pragma unroll
;     for (int j = 0; j < 4; ++j) {
;         const int crow = 32 * j + 8 * (l16 >> 2) + (l16 & 3);
;         f32x4 e4 = (f32x4){0.f, 0.f, 0.f, 0.f}, o4 = e4;
; #pragma unroll
;         for (int ks = 0; ks < 4; ++ks) {
;             const bf16x8 ae = *(const LAS bf16x8*)(Vt + crow * 136 + 32 * ks + 8 * g4), ao = *(const LAS bf16x8*)(Vt + (crow + 4) * 136 + 32 * ks + 8 * g4);
;             e4 = mfma16(ae, bw[ks], e4); o4 = mfma16(ao, bw[ks], o4);
;         }
;         const size_t off = (m0 + t) * 1024 + c0 + 32 * j + 8 * g4;
;         const v4u u4 = uu[j], g4v = gg[j];
;         v4u y;
;         y.x = pk2(bflo(u4.x) * (e4[0] + bias) * bflo(g4v.x), bfhi(u4.x) * (e4[1] + bias) * bfhi(g4v.x)); y.y = pk2(bflo(u4.y) * (e4[2] + bias) * bflo(g4v.y), bfhi(u4.y) * (e4[3] + bias) * bfhi(g4v.y));
;         y.z = pk2(bflo(u4.z) * (o4[0] + bias) * bflo(g4v.z), bfhi(u4.z) * (o4[1] + bias) * bfhi(g4v.z)); y.w = pk2(bflo(u4.w) * (o4[2] + bias) * bflo(g4v.w), bfhi(u4.w) * (o4[3] + bias) * bfhi(g4v.w));
;         *(v4u*)(Y + off) = y;
	v_add3_u32 v34, 0, v34, v54
	v_lshl_add_u64 v[50:51], v[50:51], 2, s[48:49]
	ds_read_b128 v[46:49], v34
	ds_read_b128 v[42:45], v34 offset:64
	ds_read_b128 v[38:41], v34 offset:128
	ds_read_b128 v[34:37], v34 offset:192
	v_mov_b32_e32 v50, v232
	v_lshlrev_b32_e32 v51, 1, v1
	v_and_b32_e32 v1, 3, v1
	v_and_or_b32 v1, v51, 24, v1
	v_lshlrev_b64 v[52:53], 11, v[82:83]
	v_lshl_add_u64 v[52:53], s[50:51], 0, v[52:53]
	v_mul_u32_u24_e32 v1, 0x110, v1
	v_lshl_add_u64 v[52:53], v[52:53], 0, s[0:1]
	v_mov_b32_e32 v55, v0
	v_add3_u32 v1, 0, v1, v54
	v_lshl_add_u64 v[52:53], v[52:53], 0, v[54:55]
	ds_read_b128 v[54:57], v1 offset:34816
	ds_read_b128 v[58:61], v1 offset:35904
	ds_read_b128 v[62:65], v1 offset:34880
	ds_read_b128 v[66:69], v1 offset:35968
	s_waitcnt lgkmcnt(3)
	v_mfma_f32_16x16x32_bf16 v[54:57], v[54:57], v[46:49], 0
	v_readlane_b32 s0, v254, 54
	s_add_i32 s6, s6, s0
	s_cmpk_gt_i32 s7, 0x3ff
	s_waitcnt lgkmcnt(2)
	v_mfma_f32_16x16x32_bf16 v[58:61], v[58:61], v[46:49], 0
	s_waitcnt lgkmcnt(1)
	v_mfma_f32_16x16x32_bf16 v[54:57], v[62:65], v[42:45], v[54:57]
	s_waitcnt lgkmcnt(0)
	v_mfma_f32_16x16x32_bf16 v[58:61], v[66:69], v[42:45], v[58:61]
	ds_read_b128 v[62:65], v1 offset:34944
	ds_read_b128 v[66:69], v1 offset:36032
	s_waitcnt lgkmcnt(1)
	v_mfma_f32_16x16x32_bf16 v[54:57], v[62:65], v[38:41], v[54:57]
	s_waitcnt lgkmcnt(0)
	v_mfma_f32_16x16x32_bf16 v[58:61], v[66:69], v[38:41], v[58:61]
	ds_read_b128 v[62:65], v1 offset:35008
	ds_read_b128 v[66:69], v1 offset:36096
	s_waitcnt lgkmcnt(1)
	v_mfma_f32_16x16x32_bf16 v[54:57], v[62:65], v[34:37], v[54:57]
	v_lshlrev_b32_e32 v62, 16, v30
	v_and_b32_e32 v63, 0xffff0000, v30
	v_lshlrev_b32_e32 v30, 16, v31
	s_waitcnt lgkmcnt(0)
	v_mfma_f32_16x16x32_bf16 v[58:61], v[66:69], v[34:37], v[58:61]
	v_and_b32_e32 v31, 0xffff0000, v31
	s_waitcnt vmcnt(0)
	s_nop 0
	v_pk_add_f32 v[54:55], v[50:51], v[54:55] op_sel_hi:[0,1]
	v_pk_mul_f32 v[54:55], v[54:55], v[62:63]
	v_lshlrev_b32_e32 v62, 16, v26
	v_and_b32_e32 v63, 0xffff0000, v26
	v_pk_mul_f32 v[54:55], v[54:55], v[62:63]
	s_nop 0
	v_cvt_pk_bf16_f32 v26, v54, v55
	v_pk_add_f32 v[54:55], v[50:51], v[56:57] op_sel_hi:[0,1]
	v_pk_mul_f32 v[30:31], v[54:55], v[30:31]
	v_lshlrev_b32_e32 v54, 16, v27
	v_and_b32_e32 v55, 0xffff0000, v27
	v_pk_mul_f32 v[30:31], v[30:31], v[54:55]
	v_pk_add_f32 v[54:55], v[50:51], v[58:59] op_sel_hi:[0,1]
	v_cvt_pk_bf16_f32 v27, v30, v31
	v_lshlrev_b32_e32 v30, 16, v32
	v_and_b32_e32 v31, 0xffff0000, v32
	v_pk_mul_f32 v[30:31], v[54:55], v[30:31]
	v_lshlrev_b32_e32 v54, 16, v28
	v_and_b32_e32 v55, 0xffff0000, v28
	v_pk_mul_f32 v[30:31], v[30:31], v[54:55]
	s_nop 0
	v_cvt_pk_bf16_f32 v28, v30, v31
	v_lshlrev_b32_e32 v30, 16, v33
	v_and_b32_e32 v31, 0xffff0000, v33
	v_pk_add_f32 v[32:33], v[50:51], v[60:61] op_sel_hi:[0,1]
	v_pk_mul_f32 v[30:31], v[32:33], v[30:31]
	v_lshlrev_b32_e32 v32, 16, v29
	v_and_b32_e32 v33, 0xffff0000, v29
	v_pk_mul_f32 v[30:31], v[30:31], v[32:33]
	s_nop 0
	v_cvt_pk_bf16_f32 v29, v30, v31
	global_store_dwordx4 v[52:53], v[26:29], off
	ds_read_b128 v[26:29], v1 offset:43520
	ds_read_b128 v[30:33], v1 offset:44608
	ds_read_b128 v[54:57], v1 offset:43584
	ds_read_b128 v[58:61], v1 offset:44672
	s_waitcnt lgkmcnt(3)
	v_mfma_f32_16x16x32_bf16 v[26:29], v[26:29], v[46:49], 0
	s_waitcnt lgkmcnt(2)
	v_mfma_f32_16x16x32_bf16 v[30:33], v[30:33], v[46:49], 0
	s_waitcnt lgkmcnt(1)
	v_mfma_f32_16x16x32_bf16 v[26:29], v[54:57], v[42:45], v[26:29]
	s_waitcnt lgkmcnt(0)
	v_mfma_f32_16x16x32_bf16 v[30:33], v[58:61], v[42:45], v[30:33]
	ds_read_b128 v[54:57], v1 offset:43648
	ds_read_b128 v[58:61], v1 offset:44736
	s_waitcnt lgkmcnt(1)
	v_mfma_f32_16x16x32_bf16 v[26:29], v[54:57], v[38:41], v[26:29]
	s_waitcnt lgkmcnt(0)
	v_mfma_f32_16x16x32_bf16 v[30:33], v[58:61], v[38:41], v[30:33]
	ds_read_b128 v[54:57], v1 offset:43712
	ds_read_b128 v[58:61], v1 offset:44800
	s_waitcnt lgkmcnt(1)
	v_mfma_f32_16x16x32_bf16 v[26:29], v[54:57], v[34:37], v[26:29]
	v_lshlrev_b32_e32 v54, 16, v22
	v_and_b32_e32 v55, 0xffff0000, v22
	v_lshlrev_b32_e32 v22, 16, v23
	s_waitcnt lgkmcnt(0)
	v_mfma_f32_16x16x32_bf16 v[30:33], v[58:61], v[34:37], v[30:33]
	s_nop 2
	v_add_f32_e64 v26, v50, v26
	v_add_f32_e64 v27, v50, v27
	v_pk_mul_f32 v[26:27], v[26:27], v[54:55]
	v_lshlrev_b32_e32 v54, 16, v18
	v_and_b32_e32 v55, 0xffff0000, v18
	v_pk_mul_f32 v[26:27], v[26:27], v[54:55]
	v_and_b32_e32 v23, 0xffff0000, v23
	v_cvt_pk_bf16_f32 v18, v26, v27
	v_pk_add_f32 v[26:27], v[50:51], v[28:29] op_sel_hi:[0,1]
	v_pk_mul_f32 v[22:23], v[26:27], v[22:23]
	v_lshlrev_b32_e32 v26, 16, v19
	v_and_b32_e32 v27, 0xffff0000, v19
	v_pk_mul_f32 v[22:23], v[22:23], v[26:27]
	v_pk_add_f32 v[26:27], v[50:51], v[30:31] op_sel_hi:[0,1]
	v_cvt_pk_bf16_f32 v19, v22, v23
	v_lshlrev_b32_e32 v22, 16, v24
	v_and_b32_e32 v23, 0xffff0000, v24
	v_pk_mul_f32 v[22:23], v[26:27], v[22:23]
	v_lshlrev_b32_e32 v26, 16, v20
	v_and_b32_e32 v27, 0xffff0000, v20
	v_pk_mul_f32 v[22:23], v[22:23], v[26:27]
	s_nop 0
	v_cvt_pk_bf16_f32 v20, v22, v23
	v_lshlrev_b32_e32 v22, 16, v25
	v_and_b32_e32 v23, 0xffff0000, v25
	v_pk_add_f32 v[24:25], v[50:51], v[32:33] op_sel_hi:[0,1]
	v_pk_mul_f32 v[22:23], v[24:25], v[22:23]
	v_lshlrev_b32_e32 v24, 16, v21
	v_and_b32_e32 v25, 0xffff0000, v21
	v_pk_mul_f32 v[22:23], v[22:23], v[24:25]
	s_nop 0
	v_cvt_pk_bf16_f32 v21, v22, v23
	global_store_dwordx4 v[52:53], v[18:21], off offset:64
	ds_read_b128 v[18:21], v1 offset:52224
	ds_read_b128 v[22:25], v1 offset:53312
	ds_read_b128 v[26:29], v1 offset:52288
	ds_read_b128 v[30:33], v1 offset:53376
	s_waitcnt lgkmcnt(3)
; #define LAS __attribute__((address_space(3)))
; __device__ __forceinline__ float bflo(unsigned u) { return __uint_as_float(u << 16); }
; __device__ __forceinline__ float bfhi(unsigned u) { return __uint_as_float(u & 0xffff0000u); }
; __device__ __forceinline__ unsigned pk2(float lo, float hi) { f32x2_t v = {lo, hi}; bf16x2_t b = __builtin_convertvector(v, bf16x2_t); return __builtin_bit_cast(unsigned, b); }
; __device__ __forceinline__ f32x4 mfma16(bf16x8 a, bf16x8 b, f32x4 c) { return __builtin_amdgcn_mfma_f32_16x16x32_bf16(a, b, c, 0, 0, 0); }
; #define LBAR() do { asm volatile("s_waitcnt lgkmcnt(0)" ::: "memory"); __builtin_amdgcn_s_barrier(); asm volatile("" ::: "memory"); } while (0)
; __device__ __forceinline__ void gmlp_unit(LAS unsigned char* lds, int unit, const bf16* U, const bf16* Vb, bf16* Y, const float* vs1, const float* vs2,
;                                           const float* lnw, const float* lnb, const float* bs) {
;     ...
;     for (int j = 0; j < 4; ++j) {
;         const int crow = 32 * j + 8 * (l16 >> 2) + (l16 & 3);
;         f32x4 e4 = (f32x4){0.f, 0.f, 0.f, 0.f}, o4 = e4;
; #pragma unroll
;         for (int ks = 0; ks < 4; ++ks) {
;             const bf16x8 ae = *(const LAS bf16x8*)(Vt + crow * 136 + 32 * ks + 8 * g4), ao = *(const LAS bf16x8*)(Vt + (crow + 4) * 136 + 32 * ks + 8 * g4);
;             e4 = mfma16(ae, bw[ks], e4); o4 = mfma16(ao, bw[ks], o4);
;         }
;         const size_t off = (m0 + t) * 1024 + c0 + 32 * j + 8 * g4;
;         const v4u u4 = uu[j], g4v = gg[j];
;         v4u y;
;         y.x = pk2(bflo(u4.x) * (e4[0] + bias) * bflo(g4v.x), bfhi(u4.x) * (e4[1] + bias) * bfhi(g4v.x)); y.y = pk2(bflo(u4.y) * (e4[2] + bias) * bflo(g4v.y), bfhi(u4.y) * (e4[3] + bias) * bfhi(g4v.y));
;         y.z = pk2(bflo(u4.z) * (o4[0] + bias) * bflo(g4v.z), bfhi(u4.z) * (o4[1] + bias) * bfhi(g4v.z)); y.w = pk2(bflo(u4.w) * (o4[2] + bias) * bflo(g4v.w), bfhi(u4.w) * (o4[3] + bias) * bfhi(g4v.w));
;         *(v4u*)(Y + off) = y;
;     }
;     LBAR();
	v_mfma_f32_16x16x32_bf16 v[18:21], v[18:21], v[46:49], 0
	s_waitcnt lgkmcnt(2)
	v_mfma_f32_16x16x32_bf16 v[22:25], v[22:25], v[46:49], 0
	s_waitcnt lgkmcnt(1)
	v_mfma_f32_16x16x32_bf16 v[18:21], v[26:29], v[42:45], v[18:21]
	s_waitcnt lgkmcnt(0)
	v_mfma_f32_16x16x32_bf16 v[22:25], v[30:33], v[42:45], v[22:25]
	ds_read_b128 v[26:29], v1 offset:52352
	ds_read_b128 v[30:33], v1 offset:53440
	s_waitcnt lgkmcnt(1)
	v_mfma_f32_16x16x32_bf16 v[18:21], v[26:29], v[38:41], v[18:21]
	s_waitcnt lgkmcnt(0)
	v_mfma_f32_16x16x32_bf16 v[22:25], v[30:33], v[38:41], v[22:25]
	ds_read_b128 v[26:29], v1 offset:52416
	ds_read_b128 v[30:33], v1 offset:53504
	s_waitcnt lgkmcnt(1)
	v_mfma_f32_16x16x32_bf16 v[18:21], v[26:29], v[34:37], v[18:21]
	v_lshlrev_b32_e32 v26, 16, v14
	v_and_b32_e32 v27, 0xffff0000, v14
	v_lshlrev_b32_e32 v14, 16, v15
	s_waitcnt lgkmcnt(0)
	v_mfma_f32_16x16x32_bf16 v[22:25], v[30:33], v[34:37], v[22:25]
	s_nop 2
	v_add_f32_e64 v18, v50, v18
	v_add_f32_e64 v19, v50, v19
	v_pk_mul_f32 v[18:19], v[18:19], v[26:27]
	v_lshlrev_b32_e32 v26, 16, v10
	v_and_b32_e32 v27, 0xffff0000, v10
	v_pk_mul_f32 v[18:19], v[18:19], v[26:27]
	v_and_b32_e32 v15, 0xffff0000, v15
	v_cvt_pk_bf16_f32 v10, v18, v19
	v_pk_add_f32 v[18:19], v[50:51], v[20:21] op_sel_hi:[0,1]
	v_pk_mul_f32 v[14:15], v[18:19], v[14:15]
	v_lshlrev_b32_e32 v18, 16, v11
	v_and_b32_e32 v19, 0xffff0000, v11
	v_pk_mul_f32 v[14:15], v[14:15], v[18:19]
	v_pk_add_f32 v[18:19], v[50:51], v[22:23] op_sel_hi:[0,1]
	v_cvt_pk_bf16_f32 v11, v14, v15
	v_lshlrev_b32_e32 v14, 16, v16
	v_and_b32_e32 v15, 0xffff0000, v16
	v_pk_mul_f32 v[14:15], v[18:19], v[14:15]
	v_lshlrev_b32_e32 v18, 16, v12
	v_and_b32_e32 v19, 0xffff0000, v12
	v_pk_mul_f32 v[14:15], v[14:15], v[18:19]
	s_nop 0
	v_cvt_pk_bf16_f32 v12, v14, v15
	v_lshlrev_b32_e32 v14, 16, v17
	v_and_b32_e32 v15, 0xffff0000, v17
	v_pk_add_f32 v[16:17], v[50:51], v[24:25] op_sel_hi:[0,1]
	v_pk_mul_f32 v[14:15], v[16:17], v[14:15]
	v_lshlrev_b32_e32 v16, 16, v13
	v_and_b32_e32 v17, 0xffff0000, v13
	v_pk_mul_f32 v[14:15], v[14:15], v[16:17]
	s_nop 0
	v_cvt_pk_bf16_f32 v13, v14, v15
	global_store_dwordx4 v[52:53], v[10:13], off offset:128
	ds_read_b128 v[10:13], v1 offset:60928
	ds_read_b128 v[14:17], v1 offset:62016
	ds_read_b128 v[18:21], v1 offset:60992
	ds_read_b128 v[22:25], v1 offset:62080
	s_waitcnt lgkmcnt(3)
	v_mfma_f32_16x16x32_bf16 v[10:13], v[10:13], v[46:49], 0
	s_waitcnt lgkmcnt(2)
	v_mfma_f32_16x16x32_bf16 v[14:17], v[14:17], v[46:49], 0
	s_waitcnt lgkmcnt(1)
	v_mfma_f32_16x16x32_bf16 v[10:13], v[18:21], v[42:45], v[10:13]
	s_waitcnt lgkmcnt(0)
	v_mfma_f32_16x16x32_bf16 v[14:17], v[22:25], v[42:45], v[14:17]
	ds_read_b128 v[18:21], v1 offset:61056
	ds_read_b128 v[22:25], v1 offset:62144
	s_waitcnt lgkmcnt(1)
	v_mfma_f32_16x16x32_bf16 v[10:13], v[18:21], v[38:41], v[10:13]
	s_waitcnt lgkmcnt(0)
	v_mfma_f32_16x16x32_bf16 v[14:17], v[22:25], v[38:41], v[14:17]
	ds_read_b128 v[18:21], v1 offset:61120
	ds_read_b128 v[22:25], v1 offset:62208
	s_waitcnt lgkmcnt(1)
	v_mfma_f32_16x16x32_bf16 v[10:13], v[18:21], v[34:37], v[10:13]
	v_lshlrev_b32_e32 v18, 16, v6
	v_and_b32_e32 v19, 0xffff0000, v6
	v_lshlrev_b32_e32 v6, 16, v7
	s_waitcnt lgkmcnt(0)
	v_mfma_f32_16x16x32_bf16 v[14:17], v[22:25], v[34:37], v[14:17]
	s_nop 2
	v_add_f32_e64 v10, v50, v10
	v_add_f32_e64 v11, v50, v11
	v_pk_mul_f32 v[10:11], v[10:11], v[18:19]
	v_lshlrev_b32_e32 v18, 16, v2
	v_and_b32_e32 v19, 0xffff0000, v2
	v_pk_mul_f32 v[10:11], v[10:11], v[18:19]
	v_and_b32_e32 v7, 0xffff0000, v7
	v_cvt_pk_bf16_f32 v2, v10, v11
	v_pk_add_f32 v[10:11], v[50:51], v[12:13] op_sel_hi:[0,1]
	v_pk_mul_f32 v[6:7], v[10:11], v[6:7]
	v_lshlrev_b32_e32 v10, 16, v3
	v_and_b32_e32 v11, 0xffff0000, v3
	v_pk_mul_f32 v[6:7], v[6:7], v[10:11]
	v_pk_add_f32 v[10:11], v[50:51], v[14:15] op_sel_hi:[0,1]
	v_cvt_pk_bf16_f32 v3, v6, v7
	v_lshlrev_b32_e32 v6, 16, v8
	v_and_b32_e32 v7, 0xffff0000, v8
	v_pk_mul_f32 v[6:7], v[10:11], v[6:7]
	v_lshlrev_b32_e32 v10, 16, v4
	v_and_b32_e32 v11, 0xffff0000, v4
	v_pk_mul_f32 v[6:7], v[6:7], v[10:11]
	s_nop 0
	v_cvt_pk_bf16_f32 v4, v6, v7
	v_lshlrev_b32_e32 v6, 16, v9
	v_and_b32_e32 v7, 0xffff0000, v9
	v_pk_add_f32 v[8:9], v[50:51], v[16:17] op_sel_hi:[0,1]
	v_pk_mul_f32 v[6:7], v[8:9], v[6:7]
	v_lshlrev_b32_e32 v8, 16, v5
	v_and_b32_e32 v9, 0xffff0000, v5
	v_pk_mul_f32 v[6:7], v[6:7], v[8:9]
	s_nop 0
	v_cvt_pk_bf16_f32 v5, v6, v7
	global_store_dwordx4 v[52:53], v[2:5], off offset:192
	s_waitcnt lgkmcnt(0)
	s_barrier
	s_cbranch_scc1 .LBB0_762
